# GEMM K-loops (4 of 7): loop-edge scalar work moved into the last MFMA block, off the ds_read-heavy load segment
# speedup vs baseline: 1.0051x; 1.0014x over previous
; #define PG8_STAGE(bufoff, gbase, voff) do { _Pragma("unroll") for (int _i = 0; _i < 2; ++_i) \
;         __builtin_amdgcn_global_load_lds((const unsigned*)((const char*)(gbase) + (voff)[_i]), (PG8_LAS unsigned*)(lds + (bufoff) + ldsw + _i * 8192), 16, 0, 0); } while (0)
; #define PG8_LDA(dst, b, h) do { _Pragma("unroll") for (int m = 0; m < 4; ++m) _Pragma("unroll") for (int k = 0; k < 2; ++k) dst[m][k] = *(const PG8_LAS bf16x8*)(lds + PG8_SA(b, h) + aoff + m * 2048 + k * 1024); } while (0)
; #define PG8_LDB(dst, b, h) do { _Pragma("unroll") for (int n = 0; n < 2; ++n) _Pragma("unroll") for (int k = 0; k < 2; ++k) dst[n][k] = *(const PG8_LAS bf16x8*)(lds + PG8_SB(b, h) + boff + n * 2048 + k * 1024); } while (0)
; #define PG8_MMA(ai, bj, At, Bt) do { __builtin_amdgcn_s_setprio(1); _Pragma("unroll") for (int m = 0; m < 4; ++m) _Pragma("unroll") for (int n = 0; n < 2; ++n) _Pragma("unroll") for (int k = 0; k < 2; ++k) \
;         acc[ai][bj][m][n] = __builtin_amdgcn_mfma_f32_16x16x32_bf16(Bt[n][k], At[m][k], acc[ai][bj][m][n], 0, 0, 0); __builtin_amdgcn_s_setprio(0); } while (0)
; #define PG8_WAIT_V(n) asm volatile("s_waitcnt vmcnt(" #n ")" ::: "memory")
; #define PG8_WAIT_L(n) asm volatile("s_waitcnt lgkmcnt(" #n ")" ::: "memory")
; #define PG8_BAR __builtin_amdgcn_s_barrier()
; #define PG8_SCHED __builtin_amdgcn_sched_barrier(0)
; template <class Epi, class Sched, bool ALIGN_EPI = false, bool SP2 = false>
; __device__ __forceinline__ void gemm_phase(PG8_LAS unsigned char* lds, const Gemm g, const Sched& S, const Epi& E) {
;     ...
;             PG8_LDB(B0, 0, 0); PG8_LDB(B1, 0, 1); PG8_SCHED; PG8_LDA(At, 0, 0); PG8_STAGE(PG8_SA(1, 1), a1 + hstepA, voffA);
;             PG8_WAIT_V(8); PG8_WAIT_L(0); PG8_BAR; PG8_MMA(0, 0, At, B0); PG8_MMA(0, 1, At, B1); PG8_BAR; PG8_SCHED;
;             PG8_LDA(At, 0, 1); PG8_STAGE(PG8_SB(0, 0), b2, voffB); PG8_STAGE(PG8_SB(0, 1), b2 + hstepB, voffB); PG8_STAGE(PG8_SA(0, 0), a2, voffA);
;             PG8_WAIT_V(8); PG8_WAIT_L(0); PG8_BAR; PG8_MMA(1, 0, At, B0); PG8_MMA(1, 1, At, B1); PG8_BAR; PG8_SCHED;
.Lgk_146:
	ds_read_b128 v[164:167], v130
	ds_read_b128 v[168:171], v130 offset:1024
	ds_read_b128 v[186:189], v130 offset:2048
	ds_read_b128 v[190:193], v130 offset:3072
	v_add_u32_e32 v130, s81, v161
	ds_read_b128 v[198:201], v130
	ds_read_b128 v[202:205], v130 offset:1024
	ds_read_b128 v[206:209], v130 offset:2048
	ds_read_b128 v[210:213], v130 offset:3072
	v_lshl_add_u64 v[172:173], s[46:47], 0, v[156:157]
	s_add_i32 m0, s9, 0xc000
	ds_read_b128 v[214:217], v163
	ds_read_b128 v[218:221], v163 offset:1024
	ds_read_b128 v[222:225], v163 offset:2048
	ds_read_b128 v[226:229], v163 offset:3072
	ds_read_b128 v[230:233], v163 offset:4096
	ds_read_b128 v[234:237], v163 offset:5120
	ds_read_b128 v[238:241], v163 offset:6144
	ds_read_b128 v[242:245], v163 offset:7168
	global_load_lds_dwordx4 v[172:173], off
	v_lshl_add_u64 v[172:173], s[46:47], 0, v[158:159]
	s_add_i32 m0, s9, 0xe000
	s_nop 0
	global_load_lds_dwordx4 v[172:173], off
	s_waitcnt vmcnt(8)
	s_waitcnt lgkmcnt(0)
	s_barrier
	s_setprio 1
	s_waitcnt lgkmcnt(0)
	v_mfma_f32_16x16x32_bf16 v[126:129], v[164:167], v[214:217], v[126:129]
	v_mfma_f32_16x16x32_bf16 v[122:125], v[186:189], v[214:217], v[122:125]
	v_mfma_f32_16x16x32_bf16 v[118:121], v[164:167], v[222:225], v[118:121]
	v_mfma_f32_16x16x32_bf16 v[114:117], v[186:189], v[222:225], v[114:117]
	v_mfma_f32_16x16x32_bf16 v[102:105], v[164:167], v[230:233], v[102:105]
	v_mfma_f32_16x16x32_bf16 v[98:101], v[186:189], v[230:233], v[98:101]
	v_mfma_f32_16x16x32_bf16 v[86:89], v[164:167], v[238:241], v[86:89]
	v_mfma_f32_16x16x32_bf16 v[82:85], v[186:189], v[238:241], v[82:85]
	v_mfma_f32_16x16x32_bf16 v[126:129], v[168:171], v[218:221], v[126:129]
	v_mfma_f32_16x16x32_bf16 v[122:125], v[190:193], v[218:221], v[122:125]
	v_mfma_f32_16x16x32_bf16 v[118:121], v[168:171], v[226:229], v[118:121]
	v_mfma_f32_16x16x32_bf16 v[114:117], v[190:193], v[226:229], v[114:117]
	v_mfma_f32_16x16x32_bf16 v[102:105], v[168:171], v[234:237], v[102:105]
	v_mfma_f32_16x16x32_bf16 v[98:101], v[190:193], v[234:237], v[98:101]
	v_mfma_f32_16x16x32_bf16 v[86:89], v[168:171], v[242:245], v[86:89]
	v_mfma_f32_16x16x32_bf16 v[82:85], v[190:193], v[242:245], v[82:85]
	s_setprio 0
	s_setprio 1
	v_mfma_f32_16x16x32_bf16 v[110:113], v[198:201], v[214:217], v[110:113]
	v_mfma_f32_16x16x32_bf16 v[106:109], v[206:209], v[214:217], v[106:109]
	v_mfma_f32_16x16x32_bf16 v[94:97], v[198:201], v[222:225], v[94:97]
	v_mfma_f32_16x16x32_bf16 v[90:93], v[206:209], v[222:225], v[90:93]
	v_mfma_f32_16x16x32_bf16 v[78:81], v[198:201], v[230:233], v[78:81]
	v_mfma_f32_16x16x32_bf16 v[74:77], v[206:209], v[230:233], v[74:77]
	v_mfma_f32_16x16x32_bf16 v[70:73], v[198:201], v[238:241], v[70:73]
	v_mfma_f32_16x16x32_bf16 v[66:69], v[206:209], v[238:241], v[66:69]
	v_mfma_f32_16x16x32_bf16 v[110:113], v[202:205], v[218:221], v[110:113]
	v_mfma_f32_16x16x32_bf16 v[106:109], v[210:213], v[218:221], v[106:109]
	v_mfma_f32_16x16x32_bf16 v[94:97], v[202:205], v[226:229], v[94:97]
	v_mfma_f32_16x16x32_bf16 v[90:93], v[210:213], v[226:229], v[90:93]
	v_mfma_f32_16x16x32_bf16 v[78:81], v[202:205], v[234:237], v[78:81]
	v_mfma_f32_16x16x32_bf16 v[74:77], v[210:213], v[234:237], v[74:77]
	v_mfma_f32_16x16x32_bf16 v[70:73], v[202:205], v[242:245], v[70:73]
	v_mfma_f32_16x16x32_bf16 v[66:69], v[210:213], v[242:245], v[66:69]
	s_setprio 0
	s_barrier
	s_add_i32 s10, s69, s8
	v_lshl_add_u64 v[172:173], s[48:49], 0, v[0:1]
	s_mov_b32 m0, s10
	ds_read_b128 v[214:217], v163 offset:16384
	ds_read_b128 v[218:221], v163 offset:17408
	ds_read_b128 v[222:225], v163 offset:18432
	ds_read_b128 v[226:229], v163 offset:19456
	ds_read_b128 v[230:233], v163 offset:20480
	ds_read_b128 v[234:237], v163 offset:21504
	ds_read_b128 v[238:241], v163 offset:22528
	ds_read_b128 v[242:245], v163 offset:23552
	global_load_lds_dwordx4 v[172:173], off
	s_add_i32 m0, s10, 0x2000
	s_add_u32 s10, s48, 0x40000
	v_lshl_add_u64 v[246:247], s[48:49], 0, v[150:151]
	s_addc_u32 s11, s49, 0
	s_add_i32 s69, s81, s8
	global_load_lds_dwordx4 v[246:247], off
	v_lshl_add_u64 v[248:249], s[10:11], 0, v[0:1]
	s_mov_b32 m0, s69
	v_lshl_add_u64 v[130:131], s[50:51], 0, v[152:153]
	global_load_lds_dwordx4 v[248:249], off
	v_lshl_add_u64 v[248:249], s[10:11], 0, v[150:151]
	s_add_i32 m0, s69, 0x2000
	s_nop 0
	global_load_lds_dwordx4 v[248:249], off
	v_lshl_add_u64 v[248:249], s[50:51], 0, v[154:155]
	s_mov_b32 m0, s9
	s_nop 0
	global_load_lds_dwordx4 v[248:249], off
	s_mov_b32 m0, s30
	s_nop 0
	global_load_lds_dwordx4 v[130:131], off
	s_waitcnt vmcnt(8)
	s_waitcnt lgkmcnt(0)
	s_barrier
; #define PG8_STAGE(bufoff, gbase, voff) do { _Pragma("unroll") for (int _i = 0; _i < 2; ++_i) \
;         __builtin_amdgcn_global_load_lds((const unsigned*)((const char*)(gbase) + (voff)[_i]), (PG8_LAS unsigned*)(lds + (bufoff) + ldsw + _i * 8192), 16, 0, 0); } while (0)
; #define PG8_LDA(dst, b, h) do { _Pragma("unroll") for (int m = 0; m < 4; ++m) _Pragma("unroll") for (int k = 0; k < 2; ++k) dst[m][k] = *(const PG8_LAS bf16x8*)(lds + PG8_SA(b, h) + aoff + m * 2048 + k * 1024); } while (0)
; #define PG8_LDB(dst, b, h) do { _Pragma("unroll") for (int n = 0; n < 2; ++n) _Pragma("unroll") for (int k = 0; k < 2; ++k) dst[n][k] = *(const PG8_LAS bf16x8*)(lds + PG8_SB(b, h) + boff + n * 2048 + k * 1024); } while (0)
; #define PG8_MMA(ai, bj, At, Bt) do { __builtin_amdgcn_s_setprio(1); _Pragma("unroll") for (int m = 0; m < 4; ++m) _Pragma("unroll") for (int n = 0; n < 2; ++n) _Pragma("unroll") for (int k = 0; k < 2; ++k) \
;         acc[ai][bj][m][n] = __builtin_amdgcn_mfma_f32_16x16x32_bf16(Bt[n][k], At[m][k], acc[ai][bj][m][n], 0, 0, 0); __builtin_amdgcn_s_setprio(0); } while (0)
; #define PG8_WAIT_V(n) asm volatile("s_waitcnt vmcnt(" #n ")" ::: "memory")
; #define PG8_WAIT_L(n) asm volatile("s_waitcnt lgkmcnt(" #n ")" ::: "memory")
; #define PG8_BAR __builtin_amdgcn_s_barrier()
; #define PG8_SCHED __builtin_amdgcn_sched_barrier(0)
; template <class Epi, class Sched, bool ALIGN_EPI = false, bool SP2 = false>
; __device__ __forceinline__ void gemm_phase(PG8_LAS unsigned char* lds, const Gemm g, const Sched& S, const Epi& E) {
;     ...
;             PG8_WAIT_V(8); PG8_WAIT_L(0); PG8_BAR; PG8_MMA(1, 0, At, B0); PG8_MMA(1, 1, At, B1); PG8_BAR; PG8_SCHED;
;             PG8_LDB(B0, 1, 0); PG8_LDB(B1, 1, 1); PG8_SCHED; PG8_LDA(At, 1, 0); PG8_STAGE(PG8_SA(0, 1), a2 + hstepA, voffA);
;             PG8_WAIT_V(8); PG8_WAIT_L(0); PG8_BAR; PG8_MMA(0, 0, At, B0); PG8_MMA(0, 1, At, B1); PG8_BAR; PG8_SCHED;
	s_setprio 1
	s_waitcnt lgkmcnt(0)
	v_mfma_f32_16x16x32_bf16 v[62:65], v[164:167], v[214:217], v[62:65]
	v_mfma_f32_16x16x32_bf16 v[58:61], v[186:189], v[214:217], v[58:61]
	v_mfma_f32_16x16x32_bf16 v[54:57], v[164:167], v[222:225], v[54:57]
	v_mfma_f32_16x16x32_bf16 v[50:53], v[186:189], v[222:225], v[50:53]
	v_mfma_f32_16x16x32_bf16 v[38:41], v[164:167], v[230:233], v[38:41]
	v_mfma_f32_16x16x32_bf16 v[34:37], v[186:189], v[230:233], v[34:37]
	v_mfma_f32_16x16x32_bf16 v[22:25], v[164:167], v[238:241], v[22:25]
	v_mfma_f32_16x16x32_bf16 v[18:21], v[186:189], v[238:241], v[18:21]
	v_mfma_f32_16x16x32_bf16 v[62:65], v[168:171], v[218:221], v[62:65]
	v_mfma_f32_16x16x32_bf16 v[58:61], v[190:193], v[218:221], v[58:61]
	v_mfma_f32_16x16x32_bf16 v[54:57], v[168:171], v[226:229], v[54:57]
	v_mfma_f32_16x16x32_bf16 v[50:53], v[190:193], v[226:229], v[50:53]
	v_mfma_f32_16x16x32_bf16 v[38:41], v[168:171], v[234:237], v[38:41]
	v_mfma_f32_16x16x32_bf16 v[34:37], v[190:193], v[234:237], v[34:37]
	v_mfma_f32_16x16x32_bf16 v[22:25], v[168:171], v[242:245], v[22:25]
	v_mfma_f32_16x16x32_bf16 v[18:21], v[190:193], v[242:245], v[18:21]
	s_setprio 0
	s_setprio 1
	v_mfma_f32_16x16x32_bf16 v[46:49], v[198:201], v[214:217], v[46:49]
	v_mfma_f32_16x16x32_bf16 v[42:45], v[206:209], v[214:217], v[42:45]
	v_mfma_f32_16x16x32_bf16 v[30:33], v[198:201], v[222:225], v[30:33]
	v_mfma_f32_16x16x32_bf16 v[26:29], v[206:209], v[222:225], v[26:29]
	v_mfma_f32_16x16x32_bf16 v[14:17], v[198:201], v[230:233], v[14:17]
	v_mfma_f32_16x16x32_bf16 v[10:13], v[206:209], v[230:233], v[10:13]
	v_mfma_f32_16x16x32_bf16 v[6:9], v[198:201], v[238:241], v[6:9]
	v_mfma_f32_16x16x32_bf16 v[2:5], v[206:209], v[238:241], v[2:5]
	v_mfma_f32_16x16x32_bf16 v[46:49], v[202:205], v[218:221], v[46:49]
	v_mfma_f32_16x16x32_bf16 v[42:45], v[210:213], v[218:221], v[42:45]
	v_mfma_f32_16x16x32_bf16 v[30:33], v[202:205], v[226:229], v[30:33]
	v_mfma_f32_16x16x32_bf16 v[26:29], v[210:213], v[226:229], v[26:29]
	v_mfma_f32_16x16x32_bf16 v[14:17], v[202:205], v[234:237], v[14:17]
	v_mfma_f32_16x16x32_bf16 v[10:13], v[210:213], v[234:237], v[10:13]
	v_mfma_f32_16x16x32_bf16 v[6:9], v[202:205], v[242:245], v[6:9]
	v_mfma_f32_16x16x32_bf16 v[2:5], v[210:213], v[242:245], v[2:5]
	s_setprio 0
	s_barrier
	s_add_i32 s69, 0, 0x18000
	v_add_u32_e32 v132, s69, v161
	s_add_i32 s81, 0, 0x1c000
	ds_read_b128 v[164:167], v132
	ds_read_b128 v[168:171], v132 offset:1024
	ds_read_b128 v[186:189], v132 offset:2048
	ds_read_b128 v[190:193], v132 offset:3072
	v_add_u32_e32 v132, s81, v161
	ds_read_b128 v[198:201], v132
	ds_read_b128 v[202:205], v132 offset:1024
	ds_read_b128 v[206:209], v132 offset:2048
	ds_read_b128 v[210:213], v132 offset:3072
	s_add_u32 s10, s50, 0x40000
	s_addc_u32 s11, s51, 0
	s_mov_b32 m0, s31
	v_lshl_add_u64 v[132:133], s[10:11], 0, v[154:155]
	ds_read_b128 v[214:217], v163 offset:32768
	ds_read_b128 v[218:221], v163 offset:33792
	ds_read_b128 v[222:225], v163 offset:34816
	ds_read_b128 v[226:229], v163 offset:35840
	ds_read_b128 v[230:233], v163 offset:36864
	ds_read_b128 v[234:237], v163 offset:37888
	ds_read_b128 v[238:241], v163 offset:38912
	ds_read_b128 v[242:245], v163 offset:39936
	global_load_lds_dwordx4 v[132:133], off
	v_lshl_add_u64 v[132:133], s[10:11], 0, v[152:153]
	s_mov_b32 m0, s34
	s_nop 0
	global_load_lds_dwordx4 v[132:133], off
	s_waitcnt vmcnt(8)
	s_waitcnt lgkmcnt(0)
	s_barrier
	s_setprio 1
	s_waitcnt lgkmcnt(0)
	v_mfma_f32_16x16x32_bf16 v[126:129], v[164:167], v[214:217], v[126:129]
	v_mfma_f32_16x16x32_bf16 v[122:125], v[186:189], v[214:217], v[122:125]
	v_mfma_f32_16x16x32_bf16 v[118:121], v[164:167], v[222:225], v[118:121]
	v_mfma_f32_16x16x32_bf16 v[114:117], v[186:189], v[222:225], v[114:117]
	v_mfma_f32_16x16x32_bf16 v[102:105], v[164:167], v[230:233], v[102:105]
	v_mfma_f32_16x16x32_bf16 v[98:101], v[186:189], v[230:233], v[98:101]
	v_mfma_f32_16x16x32_bf16 v[86:89], v[164:167], v[238:241], v[86:89]
	v_mfma_f32_16x16x32_bf16 v[82:85], v[186:189], v[238:241], v[82:85]
	v_mfma_f32_16x16x32_bf16 v[126:129], v[168:171], v[218:221], v[126:129]
	v_mfma_f32_16x16x32_bf16 v[122:125], v[190:193], v[218:221], v[122:125]
	v_mfma_f32_16x16x32_bf16 v[118:121], v[168:171], v[226:229], v[118:121]
	v_mfma_f32_16x16x32_bf16 v[114:117], v[190:193], v[226:229], v[114:117]
	v_mfma_f32_16x16x32_bf16 v[102:105], v[168:171], v[234:237], v[102:105]
	v_mfma_f32_16x16x32_bf16 v[98:101], v[190:193], v[234:237], v[98:101]
	v_mfma_f32_16x16x32_bf16 v[86:89], v[168:171], v[242:245], v[86:89]
	v_mfma_f32_16x16x32_bf16 v[82:85], v[190:193], v[242:245], v[82:85]
	s_setprio 0
	s_setprio 1
	v_mfma_f32_16x16x32_bf16 v[110:113], v[198:201], v[214:217], v[110:113]
	v_mfma_f32_16x16x32_bf16 v[106:109], v[206:209], v[214:217], v[106:109]
	v_mfma_f32_16x16x32_bf16 v[94:97], v[198:201], v[222:225], v[94:97]
	v_mfma_f32_16x16x32_bf16 v[90:93], v[206:209], v[222:225], v[90:93]
	v_mfma_f32_16x16x32_bf16 v[78:81], v[198:201], v[230:233], v[78:81]
	v_mfma_f32_16x16x32_bf16 v[74:77], v[206:209], v[230:233], v[74:77]
	v_mfma_f32_16x16x32_bf16 v[70:73], v[198:201], v[238:241], v[70:73]
	v_mfma_f32_16x16x32_bf16 v[66:69], v[206:209], v[238:241], v[66:69]
	v_mfma_f32_16x16x32_bf16 v[110:113], v[202:205], v[218:221], v[110:113]
	v_mfma_f32_16x16x32_bf16 v[106:109], v[210:213], v[218:221], v[106:109]
	v_mfma_f32_16x16x32_bf16 v[94:97], v[202:205], v[226:229], v[94:97]
	v_mfma_f32_16x16x32_bf16 v[90:93], v[210:213], v[226:229], v[90:93]
	v_mfma_f32_16x16x32_bf16 v[78:81], v[202:205], v[234:237], v[78:81]
	v_mfma_f32_16x16x32_bf16 v[74:77], v[210:213], v[234:237], v[74:77]
	v_mfma_f32_16x16x32_bf16 v[70:73], v[202:205], v[242:245], v[70:73]
	v_mfma_f32_16x16x32_bf16 v[66:69], v[210:213], v[242:245], v[66:69]
	s_setprio 0
	s_barrier
; #define PG8_STAGE(bufoff, gbase, voff) do { _Pragma("unroll") for (int _i = 0; _i < 2; ++_i) \
;         __builtin_amdgcn_global_load_lds((const unsigned*)((const char*)(gbase) + (voff)[_i]), (PG8_LAS unsigned*)(lds + (bufoff) + ldsw + _i * 8192), 16, 0, 0); } while (0)
; #define PG8_LDA(dst, b, h) do { _Pragma("unroll") for (int m = 0; m < 4; ++m) _Pragma("unroll") for (int k = 0; k < 2; ++k) dst[m][k] = *(const PG8_LAS bf16x8*)(lds + PG8_SA(b, h) + aoff + m * 2048 + k * 1024); } while (0)
; #define PG8_MMA(ai, bj, At, Bt) do { __builtin_amdgcn_s_setprio(1); _Pragma("unroll") for (int m = 0; m < 4; ++m) _Pragma("unroll") for (int n = 0; n < 2; ++n) _Pragma("unroll") for (int k = 0; k < 2; ++k) \
;         acc[ai][bj][m][n] = __builtin_amdgcn_mfma_f32_16x16x32_bf16(Bt[n][k], At[m][k], acc[ai][bj][m][n], 0, 0, 0); __builtin_amdgcn_s_setprio(0); } while (0)
; #define PG8_WAIT_V(n) asm volatile("s_waitcnt vmcnt(" #n ")" ::: "memory")
; #define PG8_WAIT_L(n) asm volatile("s_waitcnt lgkmcnt(" #n ")" ::: "memory")
; #define PG8_BAR __builtin_amdgcn_s_barrier()
; #define PG8_SCHED __builtin_amdgcn_sched_barrier(0)
; template <class Epi, class Sched, bool ALIGN_EPI = false, bool SP2 = false>
; __device__ __forceinline__ void gemm_phase(PG8_LAS unsigned char* lds, const Gemm g, const Sched& S, const Epi& E) {
;     ...
;         for (int t = 0; t < nt; t += 2) {
;             const bool last = (t == nt - 2);
;             const char* a1 = cA + (size_t)(t + 1) * kstep;
;             const char* a2 = last ? nA : cA + (size_t)(t + 2) * kstep; const char* b2 = last ? nB : cB + (size_t)(t + 2) * kstep;
;     ...
;             PG8_LDA(At, 1, 1); PG8_STAGE(PG8_SB(1, 0), b3, voffB); PG8_STAGE(PG8_SB(1, 1), b3 + hstepB, voffB); PG8_STAGE(PG8_SA(1, 0), a3, voffA);
;             PG8_WAIT_V(8); PG8_WAIT_L(0); PG8_BAR; PG8_MMA(1, 0, At, B0); PG8_MMA(1, 1, At, B1); PG8_BAR; PG8_SCHED;
	s_add_i32 s10, s69, s8
	v_lshl_add_u64 v[132:133], v[172:173], 0, s[2:3]
	s_mov_b32 m0, s10
	ds_read_b128 v[214:217], v163 offset:49152
	ds_read_b128 v[218:221], v163 offset:50176
	ds_read_b128 v[222:225], v163 offset:51200
	ds_read_b128 v[226:229], v163 offset:52224
	ds_read_b128 v[230:233], v163 offset:53248
	ds_read_b128 v[234:237], v163 offset:54272
	ds_read_b128 v[238:241], v163 offset:55296
	ds_read_b128 v[242:245], v163 offset:56320
	global_load_lds_dwordx4 v[132:133], off
	s_add_i32 m0, s10, 0x2000
	s_add_u32 s10, s48, 0x40080
	v_lshl_add_u64 v[132:133], v[246:247], 0, s[2:3]
	s_addc_u32 s11, s49, 0
	s_add_i32 s48, s81, s8
	global_load_lds_dwordx4 v[132:133], off
	v_lshl_add_u64 v[132:133], s[10:11], 0, v[0:1]
	s_mov_b32 m0, s48
	v_lshl_add_u64 v[130:131], v[130:131], 0, s[2:3]
	global_load_lds_dwordx4 v[132:133], off
	v_lshl_add_u64 v[132:133], s[10:11], 0, v[150:151]
	s_add_i32 m0, s48, 0x2000
	s_nop 0
	global_load_lds_dwordx4 v[132:133], off
	v_lshl_add_u64 v[132:133], v[248:249], 0, s[2:3]
	s_mov_b32 m0, s35
	s_nop 0
	global_load_lds_dwordx4 v[132:133], off
	s_mov_b32 m0, s52
	s_nop 0
	global_load_lds_dwordx4 v[130:131], off
	s_waitcnt vmcnt(8)
	s_waitcnt lgkmcnt(0)
	s_barrier
	s_setprio 1
	s_waitcnt lgkmcnt(0)
	v_mfma_f32_16x16x32_bf16 v[62:65], v[164:167], v[214:217], v[62:65]
	v_mfma_f32_16x16x32_bf16 v[58:61], v[186:189], v[214:217], v[58:61]
	s_add_i32 s68, s68, 2
	v_mfma_f32_16x16x32_bf16 v[54:57], v[164:167], v[222:225], v[54:57]
	s_add_u32 s46, s46, 0x100
	v_mfma_f32_16x16x32_bf16 v[50:53], v[186:189], v[222:225], v[50:53]
	s_addc_u32 s47, s47, 0
	v_mfma_f32_16x16x32_bf16 v[38:41], v[164:167], v[230:233], v[38:41]
	s_add_u32 s62, s62, 0x100
	v_mfma_f32_16x16x32_bf16 v[34:37], v[186:189], v[230:233], v[34:37]
	s_addc_u32 s63, s63, 0
	v_mfma_f32_16x16x32_bf16 v[22:25], v[164:167], v[238:241], v[22:25]
	s_add_u32 s10, s46, 0xfffc0080
	v_mfma_f32_16x16x32_bf16 v[18:21], v[186:189], v[238:241], v[18:21]
	s_addc_u32 s11, s47, -1
	v_mfma_f32_16x16x32_bf16 v[62:65], v[168:171], v[218:221], v[62:65]
	s_add_i32 s69, 0, 0x10000
	v_mfma_f32_16x16x32_bf16 v[58:61], v[190:193], v[218:221], v[58:61]
	s_cmp_eq_u32 s68, 12
	v_mfma_f32_16x16x32_bf16 v[54:57], v[168:171], v[226:229], v[54:57]
	s_cselect_b32 s51, s41, s11
	v_mfma_f32_16x16x32_bf16 v[50:53], v[190:193], v[226:229], v[50:53]
	s_cselect_b32 s50, s57, s10
	v_mfma_f32_16x16x32_bf16 v[38:41], v[168:171], v[234:237], v[38:41]
	v_add_u32_e32 v130, s69, v161
	v_mfma_f32_16x16x32_bf16 v[34:37], v[190:193], v[234:237], v[34:37]
	s_cselect_b32 s49, s4, s63
	v_mfma_f32_16x16x32_bf16 v[22:25], v[168:171], v[242:245], v[22:25]
	s_cselect_b32 s48, s39, s62
	v_mfma_f32_16x16x32_bf16 v[18:21], v[190:193], v[242:245], v[18:21]
	s_add_i32 s81, 0, 0x14000
	s_setprio 0
	s_setprio 1
	v_mfma_f32_16x16x32_bf16 v[46:49], v[198:201], v[214:217], v[46:49]
	s_cmp_gt_u32 s68, 13
	v_mfma_f32_16x16x32_bf16 v[42:45], v[206:209], v[214:217], v[42:45]
	v_mfma_f32_16x16x32_bf16 v[30:33], v[198:201], v[222:225], v[30:33]
	v_mfma_f32_16x16x32_bf16 v[26:29], v[206:209], v[222:225], v[26:29]
	v_mfma_f32_16x16x32_bf16 v[14:17], v[198:201], v[230:233], v[14:17]
	v_mfma_f32_16x16x32_bf16 v[10:13], v[206:209], v[230:233], v[10:13]
	v_mfma_f32_16x16x32_bf16 v[6:9], v[198:201], v[238:241], v[6:9]
	v_mfma_f32_16x16x32_bf16 v[2:5], v[206:209], v[238:241], v[2:5]
	v_mfma_f32_16x16x32_bf16 v[46:49], v[202:205], v[218:221], v[46:49]
	v_mfma_f32_16x16x32_bf16 v[42:45], v[210:213], v[218:221], v[42:45]
	v_mfma_f32_16x16x32_bf16 v[30:33], v[202:205], v[226:229], v[30:33]
	v_mfma_f32_16x16x32_bf16 v[26:29], v[210:213], v[226:229], v[26:29]
	v_mfma_f32_16x16x32_bf16 v[14:17], v[202:205], v[234:237], v[14:17]
	v_mfma_f32_16x16x32_bf16 v[10:13], v[210:213], v[234:237], v[10:13]
	v_mfma_f32_16x16x32_bf16 v[6:9], v[202:205], v[242:245], v[6:9]
	v_mfma_f32_16x16x32_bf16 v[2:5], v[210:213], v[242:245], v[2:5]
	s_setprio 0
	s_barrier
	s_cbranch_scc0 .Lgk_146
	s_and_b64 vcc, exec, s[20:21]
	s_cbranch_vccz .LBB0_149
	s_barrier

; #define PG8_STAGE(bufoff, gbase, voff) do { _Pragma("unroll") for (int _i = 0; _i < 2; ++_i) \
;         __builtin_amdgcn_global_load_lds((const unsigned*)((const char*)(gbase) + (voff)[_i]), (PG8_LAS unsigned*)(lds + (bufoff) + ldsw + _i * 8192), 16, 0, 0); } while (0)
; #define PG8_LDA(dst, b, h) do { _Pragma("unroll") for (int m = 0; m < 4; ++m) _Pragma("unroll") for (int k = 0; k < 2; ++k) dst[m][k] = *(const PG8_LAS bf16x8*)(lds + PG8_SA(b, h) + aoff + m * 2048 + k * 1024); } while (0)
; #define PG8_LDB(dst, b, h) do { _Pragma("unroll") for (int n = 0; n < 2; ++n) _Pragma("unroll") for (int k = 0; k < 2; ++k) dst[n][k] = *(const PG8_LAS bf16x8*)(lds + PG8_SB(b, h) + boff + n * 2048 + k * 1024); } while (0)
; #define PG8_MMA(ai, bj, At, Bt) do { __builtin_amdgcn_s_setprio(1); _Pragma("unroll") for (int m = 0; m < 4; ++m) _Pragma("unroll") for (int n = 0; n < 2; ++n) _Pragma("unroll") for (int k = 0; k < 2; ++k) \
;         acc[ai][bj][m][n] = __builtin_amdgcn_mfma_f32_16x16x32_bf16(Bt[n][k], At[m][k], acc[ai][bj][m][n], 0, 0, 0); __builtin_amdgcn_s_setprio(0); } while (0)
; #define PG8_WAIT_V(n) asm volatile("s_waitcnt vmcnt(" #n ")" ::: "memory")
; #define PG8_WAIT_L(n) asm volatile("s_waitcnt lgkmcnt(" #n ")" ::: "memory")
; #define PG8_BAR __builtin_amdgcn_s_barrier()
; #define PG8_SCHED __builtin_amdgcn_sched_barrier(0)
; template <class Epi, class Sched, bool ALIGN_EPI = false, bool SP2 = false>
; __device__ __forceinline__ void gemm_phase(PG8_LAS unsigned char* lds, const Gemm g, const Sched& S, const Epi& E) {
;     ...
;             PG8_LDB(B0, 0, 0); PG8_LDB(B1, 0, 1); PG8_SCHED; PG8_LDA(At, 0, 0); PG8_STAGE(PG8_SA(1, 1), a1 + hstepA, voffA);
;             PG8_WAIT_V(8); PG8_WAIT_L(0); PG8_BAR; PG8_MMA(0, 0, At, B0); PG8_MMA(0, 1, At, B1); PG8_BAR; PG8_SCHED;
;             PG8_LDA(At, 0, 1); PG8_STAGE(PG8_SB(0, 0), b2, voffB); PG8_STAGE(PG8_SB(0, 1), b2 + hstepB, voffB); PG8_STAGE(PG8_SA(0, 0), a2, voffA);
;             PG8_WAIT_V(8); PG8_WAIT_L(0); PG8_BAR; PG8_MMA(1, 0, At, B0); PG8_MMA(1, 1, At, B1); PG8_BAR; PG8_SCHED;
.Lgk_603:
	ds_read_b128 v[166:169], v130
	ds_read_b128 v[170:173], v130 offset:1024
	ds_read_b128 v[186:189], v130 offset:2048
	ds_read_b128 v[190:193], v130 offset:3072
	v_add_u32_e32 v130, s13, v163
	ds_read_b128 v[198:201], v130
	ds_read_b128 v[202:205], v130 offset:1024
	ds_read_b128 v[206:209], v130 offset:2048
	ds_read_b128 v[210:213], v130 offset:3072
	v_lshl_add_u64 v[130:131], s[50:51], 0, v[156:157]
	s_add_i32 m0, s31, 0xc000
	ds_read_b128 v[214:217], v165
	ds_read_b128 v[218:221], v165 offset:1024
	ds_read_b128 v[222:225], v165 offset:2048
	ds_read_b128 v[226:229], v165 offset:3072
	ds_read_b128 v[230:233], v165 offset:4096
	ds_read_b128 v[234:237], v165 offset:5120
	ds_read_b128 v[238:241], v165 offset:6144
	ds_read_b128 v[242:245], v165 offset:7168
	global_load_lds_dwordx4 v[130:131], off
	v_lshl_add_u64 v[130:131], s[50:51], 0, v[158:159]
	s_add_i32 m0, s31, 0xe000
	s_nop 0
	global_load_lds_dwordx4 v[130:131], off
	s_waitcnt vmcnt(8)
	s_waitcnt lgkmcnt(0)
	s_barrier
	s_setprio 1
	s_waitcnt lgkmcnt(0)
	v_mfma_f32_16x16x32_bf16 v[126:129], v[166:169], v[214:217], v[126:129]
	v_mfma_f32_16x16x32_bf16 v[122:125], v[186:189], v[214:217], v[122:125]
	v_mfma_f32_16x16x32_bf16 v[110:113], v[166:169], v[222:225], v[110:113]
	v_mfma_f32_16x16x32_bf16 v[106:109], v[186:189], v[222:225], v[106:109]
	v_mfma_f32_16x16x32_bf16 v[94:97], v[166:169], v[230:233], v[94:97]
	v_mfma_f32_16x16x32_bf16 v[90:93], v[186:189], v[230:233], v[90:93]
	v_mfma_f32_16x16x32_bf16 v[78:81], v[166:169], v[238:241], v[78:81]
	v_mfma_f32_16x16x32_bf16 v[74:77], v[186:189], v[238:241], v[74:77]
	v_mfma_f32_16x16x32_bf16 v[126:129], v[170:173], v[218:221], v[126:129]
	v_mfma_f32_16x16x32_bf16 v[122:125], v[190:193], v[218:221], v[122:125]
	v_mfma_f32_16x16x32_bf16 v[110:113], v[170:173], v[226:229], v[110:113]
	v_mfma_f32_16x16x32_bf16 v[106:109], v[190:193], v[226:229], v[106:109]
	v_mfma_f32_16x16x32_bf16 v[94:97], v[170:173], v[234:237], v[94:97]
	v_mfma_f32_16x16x32_bf16 v[90:93], v[190:193], v[234:237], v[90:93]
	v_mfma_f32_16x16x32_bf16 v[78:81], v[170:173], v[242:245], v[78:81]
	v_mfma_f32_16x16x32_bf16 v[74:77], v[190:193], v[242:245], v[74:77]
	s_setprio 0
	s_setprio 1
	v_mfma_f32_16x16x32_bf16 v[118:121], v[198:201], v[214:217], v[118:121]
	v_mfma_f32_16x16x32_bf16 v[114:117], v[206:209], v[214:217], v[114:117]
	v_mfma_f32_16x16x32_bf16 v[102:105], v[198:201], v[222:225], v[102:105]
	v_mfma_f32_16x16x32_bf16 v[98:101], v[206:209], v[222:225], v[98:101]
	v_mfma_f32_16x16x32_bf16 v[86:89], v[198:201], v[230:233], v[86:89]
	v_mfma_f32_16x16x32_bf16 v[82:85], v[206:209], v[230:233], v[82:85]
	v_mfma_f32_16x16x32_bf16 v[70:73], v[198:201], v[238:241], v[70:73]
	v_mfma_f32_16x16x32_bf16 v[66:69], v[206:209], v[238:241], v[66:69]
	v_mfma_f32_16x16x32_bf16 v[118:121], v[202:205], v[218:221], v[118:121]
	v_mfma_f32_16x16x32_bf16 v[114:117], v[210:213], v[218:221], v[114:117]
	v_mfma_f32_16x16x32_bf16 v[102:105], v[202:205], v[226:229], v[102:105]
	v_mfma_f32_16x16x32_bf16 v[98:101], v[210:213], v[226:229], v[98:101]
	v_mfma_f32_16x16x32_bf16 v[86:89], v[202:205], v[234:237], v[86:89]
	v_mfma_f32_16x16x32_bf16 v[82:85], v[210:213], v[234:237], v[82:85]
	v_mfma_f32_16x16x32_bf16 v[70:73], v[202:205], v[242:245], v[70:73]
	v_mfma_f32_16x16x32_bf16 v[66:69], v[210:213], v[242:245], v[66:69]
	s_setprio 0
	s_barrier
	s_add_i32 s10, s12, s30
	v_lshl_add_u64 v[130:131], s[52:53], 0, v[0:1]
	s_mov_b32 m0, s10
	ds_read_b128 v[214:217], v165 offset:16384
	ds_read_b128 v[218:221], v165 offset:17408
	ds_read_b128 v[222:225], v165 offset:18432
	ds_read_b128 v[226:229], v165 offset:19456
	ds_read_b128 v[230:233], v165 offset:20480
	ds_read_b128 v[234:237], v165 offset:21504
	ds_read_b128 v[238:241], v165 offset:22528
	ds_read_b128 v[242:245], v165 offset:23552
	global_load_lds_dwordx4 v[130:131], off
	s_add_i32 m0, s10, 0x2000
	s_add_u32 s10, s52, 0x40000
	v_lshl_add_u64 v[132:133], s[52:53], 0, v[150:151]
	s_addc_u32 s11, s53, 0
	s_add_i32 s12, s13, s30
	global_load_lds_dwordx4 v[132:133], off
	v_lshl_add_u64 v[160:161], s[10:11], 0, v[0:1]
	s_mov_b32 m0, s12
	v_lshl_add_u64 v[246:247], s[54:55], 0, v[152:153]
	global_load_lds_dwordx4 v[160:161], off
	v_lshl_add_u64 v[160:161], s[10:11], 0, v[150:151]
	s_add_i32 m0, s12, 0x2000
	s_nop 0
	global_load_lds_dwordx4 v[160:161], off
	v_lshl_add_u64 v[160:161], s[54:55], 0, v[154:155]
	s_mov_b32 m0, s31
	s_nop 0
	global_load_lds_dwordx4 v[160:161], off
	s_mov_b32 m0, s34
	s_nop 0
	global_load_lds_dwordx4 v[246:247], off
	s_waitcnt vmcnt(8)
	s_waitcnt lgkmcnt(0)
	s_barrier
; #define PG8_STAGE(bufoff, gbase, voff) do { _Pragma("unroll") for (int _i = 0; _i < 2; ++_i) \
;         __builtin_amdgcn_global_load_lds((const unsigned*)((const char*)(gbase) + (voff)[_i]), (PG8_LAS unsigned*)(lds + (bufoff) + ldsw + _i * 8192), 16, 0, 0); } while (0)
; #define PG8_LDA(dst, b, h) do { _Pragma("unroll") for (int m = 0; m < 4; ++m) _Pragma("unroll") for (int k = 0; k < 2; ++k) dst[m][k] = *(const PG8_LAS bf16x8*)(lds + PG8_SA(b, h) + aoff + m * 2048 + k * 1024); } while (0)
; #define PG8_LDB(dst, b, h) do { _Pragma("unroll") for (int n = 0; n < 2; ++n) _Pragma("unroll") for (int k = 0; k < 2; ++k) dst[n][k] = *(const PG8_LAS bf16x8*)(lds + PG8_SB(b, h) + boff + n * 2048 + k * 1024); } while (0)
; #define PG8_MMA(ai, bj, At, Bt) do { __builtin_amdgcn_s_setprio(1); _Pragma("unroll") for (int m = 0; m < 4; ++m) _Pragma("unroll") for (int n = 0; n < 2; ++n) _Pragma("unroll") for (int k = 0; k < 2; ++k) \
;         acc[ai][bj][m][n] = __builtin_amdgcn_mfma_f32_16x16x32_bf16(Bt[n][k], At[m][k], acc[ai][bj][m][n], 0, 0, 0); __builtin_amdgcn_s_setprio(0); } while (0)
; #define PG8_WAIT_V(n) asm volatile("s_waitcnt vmcnt(" #n ")" ::: "memory")
; #define PG8_WAIT_L(n) asm volatile("s_waitcnt lgkmcnt(" #n ")" ::: "memory")
; #define PG8_BAR __builtin_amdgcn_s_barrier()
; #define PG8_SCHED __builtin_amdgcn_sched_barrier(0)
; template <class Epi, class Sched, bool ALIGN_EPI = false, bool SP2 = false>
; __device__ __forceinline__ void gemm_phase(PG8_LAS unsigned char* lds, const Gemm g, const Sched& S, const Epi& E) {
;     ...
;             PG8_WAIT_V(8); PG8_WAIT_L(0); PG8_BAR; PG8_MMA(1, 0, At, B0); PG8_MMA(1, 1, At, B1); PG8_BAR; PG8_SCHED;
;             PG8_LDB(B0, 1, 0); PG8_LDB(B1, 1, 1); PG8_SCHED; PG8_LDA(At, 1, 0); PG8_STAGE(PG8_SA(0, 1), a2 + hstepA, voffA);
;             PG8_WAIT_V(8); PG8_WAIT_L(0); PG8_BAR; PG8_MMA(0, 0, At, B0); PG8_MMA(0, 1, At, B1); PG8_BAR; PG8_SCHED;
	s_setprio 1
	s_waitcnt lgkmcnt(0)
	v_mfma_f32_16x16x32_bf16 v[62:65], v[166:169], v[214:217], v[62:65]
	v_mfma_f32_16x16x32_bf16 v[58:61], v[186:189], v[214:217], v[58:61]
	v_mfma_f32_16x16x32_bf16 v[46:49], v[166:169], v[222:225], v[46:49]
	v_mfma_f32_16x16x32_bf16 v[42:45], v[186:189], v[222:225], v[42:45]
	v_mfma_f32_16x16x32_bf16 v[30:33], v[166:169], v[230:233], v[30:33]
	v_mfma_f32_16x16x32_bf16 v[26:29], v[186:189], v[230:233], v[26:29]
	v_mfma_f32_16x16x32_bf16 v[14:17], v[166:169], v[238:241], v[14:17]
	v_mfma_f32_16x16x32_bf16 v[10:13], v[186:189], v[238:241], v[10:13]
	v_mfma_f32_16x16x32_bf16 v[62:65], v[170:173], v[218:221], v[62:65]
	v_mfma_f32_16x16x32_bf16 v[58:61], v[190:193], v[218:221], v[58:61]
	v_mfma_f32_16x16x32_bf16 v[46:49], v[170:173], v[226:229], v[46:49]
	v_mfma_f32_16x16x32_bf16 v[42:45], v[190:193], v[226:229], v[42:45]
	v_mfma_f32_16x16x32_bf16 v[30:33], v[170:173], v[234:237], v[30:33]
	v_mfma_f32_16x16x32_bf16 v[26:29], v[190:193], v[234:237], v[26:29]
	v_mfma_f32_16x16x32_bf16 v[14:17], v[170:173], v[242:245], v[14:17]
	v_mfma_f32_16x16x32_bf16 v[10:13], v[190:193], v[242:245], v[10:13]
	s_setprio 0
	s_setprio 1
	v_mfma_f32_16x16x32_bf16 v[54:57], v[198:201], v[214:217], v[54:57]
	v_mfma_f32_16x16x32_bf16 v[50:53], v[206:209], v[214:217], v[50:53]
	v_mfma_f32_16x16x32_bf16 v[38:41], v[198:201], v[222:225], v[38:41]
	v_mfma_f32_16x16x32_bf16 v[34:37], v[206:209], v[222:225], v[34:37]
	v_mfma_f32_16x16x32_bf16 v[22:25], v[198:201], v[230:233], v[22:25]
	v_mfma_f32_16x16x32_bf16 v[18:21], v[206:209], v[230:233], v[18:21]
	v_mfma_f32_16x16x32_bf16 v[6:9], v[198:201], v[238:241], v[6:9]
	v_mfma_f32_16x16x32_bf16 v[2:5], v[206:209], v[238:241], v[2:5]
	v_mfma_f32_16x16x32_bf16 v[54:57], v[202:205], v[218:221], v[54:57]
	v_mfma_f32_16x16x32_bf16 v[50:53], v[210:213], v[218:221], v[50:53]
	v_mfma_f32_16x16x32_bf16 v[38:41], v[202:205], v[226:229], v[38:41]
	v_mfma_f32_16x16x32_bf16 v[34:37], v[210:213], v[226:229], v[34:37]
	v_mfma_f32_16x16x32_bf16 v[22:25], v[202:205], v[234:237], v[22:25]
	v_mfma_f32_16x16x32_bf16 v[18:21], v[210:213], v[234:237], v[18:21]
	v_mfma_f32_16x16x32_bf16 v[6:9], v[202:205], v[242:245], v[6:9]
	v_mfma_f32_16x16x32_bf16 v[2:5], v[210:213], v[242:245], v[2:5]
	s_setprio 0
	s_barrier
	s_add_i32 s12, 0, 0x18000
	s_add_i32 s13, 0, 0x1c000
	v_add_u32_e32 v190, s12, v163
	v_add_u32_e32 v210, s13, v163
	ds_read_b128 v[166:169], v190
	ds_read_b128 v[170:173], v190 offset:1024
	ds_read_b128 v[186:189], v190 offset:2048
	ds_read_b128 v[190:193], v190 offset:3072
	ds_read_b128 v[198:201], v210
	ds_read_b128 v[202:205], v210 offset:1024
	ds_read_b128 v[206:209], v210 offset:2048
	ds_read_b128 v[210:213], v210 offset:3072
	s_add_u32 s10, s54, 0x40000
	s_addc_u32 s11, s55, 0
	s_mov_b32 m0, s35
	v_lshl_add_u64 v[248:249], s[10:11], 0, v[154:155]
	ds_read_b128 v[214:217], v165 offset:32768
	ds_read_b128 v[218:221], v165 offset:33792
	ds_read_b128 v[222:225], v165 offset:34816
	ds_read_b128 v[226:229], v165 offset:35840
	ds_read_b128 v[230:233], v165 offset:36864
	ds_read_b128 v[234:237], v165 offset:37888
	ds_read_b128 v[238:241], v165 offset:38912
	ds_read_b128 v[242:245], v165 offset:39936
	global_load_lds_dwordx4 v[248:249], off
	v_lshl_add_u64 v[248:249], s[10:11], 0, v[152:153]
	s_mov_b32 m0, s56
	s_nop 0
	global_load_lds_dwordx4 v[248:249], off
	s_waitcnt vmcnt(8)
	s_waitcnt lgkmcnt(0)
	s_barrier
	s_setprio 1
	s_waitcnt lgkmcnt(0)
	v_mfma_f32_16x16x32_bf16 v[126:129], v[166:169], v[214:217], v[126:129]
	v_mfma_f32_16x16x32_bf16 v[122:125], v[186:189], v[214:217], v[122:125]
	v_mfma_f32_16x16x32_bf16 v[110:113], v[166:169], v[222:225], v[110:113]
	v_mfma_f32_16x16x32_bf16 v[106:109], v[186:189], v[222:225], v[106:109]
	v_mfma_f32_16x16x32_bf16 v[94:97], v[166:169], v[230:233], v[94:97]
	v_mfma_f32_16x16x32_bf16 v[90:93], v[186:189], v[230:233], v[90:93]
	v_mfma_f32_16x16x32_bf16 v[78:81], v[166:169], v[238:241], v[78:81]
	v_mfma_f32_16x16x32_bf16 v[74:77], v[186:189], v[238:241], v[74:77]
	v_mfma_f32_16x16x32_bf16 v[126:129], v[170:173], v[218:221], v[126:129]
	v_mfma_f32_16x16x32_bf16 v[122:125], v[190:193], v[218:221], v[122:125]
	v_mfma_f32_16x16x32_bf16 v[110:113], v[170:173], v[226:229], v[110:113]
	v_mfma_f32_16x16x32_bf16 v[106:109], v[190:193], v[226:229], v[106:109]
	v_mfma_f32_16x16x32_bf16 v[94:97], v[170:173], v[234:237], v[94:97]
	v_mfma_f32_16x16x32_bf16 v[90:93], v[190:193], v[234:237], v[90:93]
	v_mfma_f32_16x16x32_bf16 v[78:81], v[170:173], v[242:245], v[78:81]
	v_mfma_f32_16x16x32_bf16 v[74:77], v[190:193], v[242:245], v[74:77]
	s_setprio 0
	s_setprio 1
	v_mfma_f32_16x16x32_bf16 v[118:121], v[198:201], v[214:217], v[118:121]
	v_mfma_f32_16x16x32_bf16 v[114:117], v[206:209], v[214:217], v[114:117]
	v_mfma_f32_16x16x32_bf16 v[102:105], v[198:201], v[222:225], v[102:105]
	v_mfma_f32_16x16x32_bf16 v[98:101], v[206:209], v[222:225], v[98:101]
	v_mfma_f32_16x16x32_bf16 v[86:89], v[198:201], v[230:233], v[86:89]
	v_mfma_f32_16x16x32_bf16 v[82:85], v[206:209], v[230:233], v[82:85]
	v_mfma_f32_16x16x32_bf16 v[70:73], v[198:201], v[238:241], v[70:73]
	v_mfma_f32_16x16x32_bf16 v[66:69], v[206:209], v[238:241], v[66:69]
	v_mfma_f32_16x16x32_bf16 v[118:121], v[202:205], v[218:221], v[118:121]
	v_mfma_f32_16x16x32_bf16 v[114:117], v[210:213], v[218:221], v[114:117]
	v_mfma_f32_16x16x32_bf16 v[102:105], v[202:205], v[226:229], v[102:105]
	v_mfma_f32_16x16x32_bf16 v[98:101], v[210:213], v[226:229], v[98:101]
	v_mfma_f32_16x16x32_bf16 v[86:89], v[202:205], v[234:237], v[86:89]
	v_mfma_f32_16x16x32_bf16 v[82:85], v[210:213], v[234:237], v[82:85]
	v_mfma_f32_16x16x32_bf16 v[70:73], v[202:205], v[242:245], v[70:73]
	v_mfma_f32_16x16x32_bf16 v[66:69], v[210:213], v[242:245], v[66:69]
	s_setprio 0
	s_barrier
; #define PG8_STAGE(bufoff, gbase, voff) do { _Pragma("unroll") for (int _i = 0; _i < 2; ++_i) \
;         __builtin_amdgcn_global_load_lds((const unsigned*)((const char*)(gbase) + (voff)[_i]), (PG8_LAS unsigned*)(lds + (bufoff) + ldsw + _i * 8192), 16, 0, 0); } while (0)
; #define PG8_LDA(dst, b, h) do { _Pragma("unroll") for (int m = 0; m < 4; ++m) _Pragma("unroll") for (int k = 0; k < 2; ++k) dst[m][k] = *(const PG8_LAS bf16x8*)(lds + PG8_SA(b, h) + aoff + m * 2048 + k * 1024); } while (0)
; #define PG8_LDB(dst, b, h) do { _Pragma("unroll") for (int n = 0; n < 2; ++n) _Pragma("unroll") for (int k = 0; k < 2; ++k) dst[n][k] = *(const PG8_LAS bf16x8*)(lds + PG8_SB(b, h) + boff + n * 2048 + k * 1024); } while (0)
; template <class Epi, class Sched, bool ALIGN_EPI = false, bool SP2 = false>
; __device__ __forceinline__ void gemm_phase(PG8_LAS unsigned char* lds, const Gemm g, const Sched& S, const Epi& E) {
;     ...
;         for (int t = 0; t < nt; t += 2) {
;             const bool last = (t == nt - 2);
;             const char* a1 = cA + (size_t)(t + 1) * kstep;
;             const char* a2 = last ? nA : cA + (size_t)(t + 2) * kstep; const char* b2 = last ? nB : cB + (size_t)(t + 2) * kstep;
;             const char* a3 = a2 + kstep; const char* b3 = b2 + kstep;
;             if (last && has_next) S.a_ready(nxt);
;             if constexpr (SP2) {
;             PG8_LDB(B0, 0, 0); PG8_LDB(B1, 0, 1); PG8_SCHED; PG8_LDA(At, 0, 0); PG8_STAGE(PG8_SA(1, 1), a1 + hstepA, voffA);
;             PG8_WAIT_V(8); PG8_WAIT_L(0); PG8_BAR; PG8_MMA(0, 0, At, B0); PG8_MMA(0, 1, At, B1); PG8_BAR; PG8_SCHED;
;             PG8_LDA(At, 0, 1); PG8_STAGE(PG8_SB(0, 0), b2, voffB); PG8_STAGE(PG8_SB(0, 1), b2 + hstepB, voffB); PG8_STAGE(PG8_SA(0, 0), a2, voffA);
;             PG8_WAIT_V(8); PG8_WAIT_L(0); PG8_BAR; PG8_MMA(1, 0, At, B0); PG8_MMA(1, 1, At, B1); PG8_BAR; PG8_SCHED;
;             PG8_LDB(B0, 1, 0); PG8_LDB(B1, 1, 1); PG8_SCHED; PG8_LDA(At, 1, 0); PG8_STAGE(PG8_SA(0, 1), a2 + hstepA, voffA);
;             PG8_WAIT_V(8); PG8_WAIT_L(0); PG8_BAR; PG8_MMA(0, 0, At, B0); PG8_MMA(0, 1, At, B1); PG8_BAR; PG8_SCHED;
;             PG8_LDA(At, 1, 1); PG8_STAGE(PG8_SB(1, 0), b3, voffB); PG8_STAGE(PG8_SB(1, 1), b3 + hstepB, voffB); PG8_STAGE(PG8_SA(1, 0), a3, voffA);
;             PG8_WAIT_V(8); PG8_WAIT_L(0); PG8_BAR; PG8_MMA(1, 0, At, B0); PG8_MMA(1, 1, At, B1); PG8_BAR; PG8_SCHED;
	s_add_i32 s10, s12, s30
	v_lshl_add_u64 v[130:131], v[130:131], 0, s[2:3]
	s_mov_b32 m0, s10
	ds_read_b128 v[214:217], v165 offset:49152
	ds_read_b128 v[218:221], v165 offset:50176
	ds_read_b128 v[222:225], v165 offset:51200
	ds_read_b128 v[226:229], v165 offset:52224
	ds_read_b128 v[230:233], v165 offset:53248
	ds_read_b128 v[234:237], v165 offset:54272
	ds_read_b128 v[238:241], v165 offset:55296
	ds_read_b128 v[242:245], v165 offset:56320
	global_load_lds_dwordx4 v[130:131], off
	s_add_i32 m0, s10, 0x2000
	s_add_u32 s10, s52, 0x40080
	v_lshl_add_u64 v[130:131], v[132:133], 0, s[2:3]
	s_addc_u32 s11, s53, 0
	s_add_i32 s12, s13, s30
	global_load_lds_dwordx4 v[130:131], off
	v_lshl_add_u64 v[130:131], s[10:11], 0, v[0:1]
	s_mov_b32 m0, s12
	s_nop 0
	global_load_lds_dwordx4 v[130:131], off
	v_lshl_add_u64 v[130:131], s[10:11], 0, v[150:151]
	s_add_i32 m0, s12, 0x2000
	s_nop 0
	global_load_lds_dwordx4 v[130:131], off
	v_lshl_add_u64 v[130:131], v[160:161], 0, s[2:3]
	s_mov_b32 m0, s57
	s_nop 0
	global_load_lds_dwordx4 v[130:131], off
	v_lshl_add_u64 v[130:131], v[246:247], 0, s[2:3]
	s_mov_b32 m0, s62
	s_nop 0
	global_load_lds_dwordx4 v[130:131], off
	s_waitcnt vmcnt(8)
	s_waitcnt lgkmcnt(0)
	s_barrier
	s_setprio 1
	s_waitcnt lgkmcnt(0)
	v_mfma_f32_16x16x32_bf16 v[62:65], v[166:169], v[214:217], v[62:65]
	v_mfma_f32_16x16x32_bf16 v[58:61], v[186:189], v[214:217], v[58:61]
	s_add_i32 s95, s95, 2
	v_mfma_f32_16x16x32_bf16 v[46:49], v[166:169], v[222:225], v[46:49]
	s_add_u32 s50, s50, 0x100
	v_mfma_f32_16x16x32_bf16 v[42:45], v[186:189], v[222:225], v[42:45]
	s_addc_u32 s51, s51, 0
	v_mfma_f32_16x16x32_bf16 v[30:33], v[166:169], v[230:233], v[30:33]
	s_add_u32 s91, s91, 0x100
	v_mfma_f32_16x16x32_bf16 v[26:29], v[186:189], v[230:233], v[26:29]
	s_addc_u32 s94, s94, 0
	v_mfma_f32_16x16x32_bf16 v[14:17], v[166:169], v[238:241], v[14:17]
	s_add_u32 s10, s50, 0xfffc0080
	v_mfma_f32_16x16x32_bf16 v[10:13], v[186:189], v[238:241], v[10:13]
	s_addc_u32 s11, s51, -1
	v_mfma_f32_16x16x32_bf16 v[62:65], v[170:173], v[218:221], v[62:65]
	s_add_i32 s12, 0, 0x10000
	v_mfma_f32_16x16x32_bf16 v[58:61], v[190:193], v[218:221], v[58:61]
	s_cmp_eq_u32 s95, 12
	v_mfma_f32_16x16x32_bf16 v[46:49], v[170:173], v[226:229], v[46:49]
	s_cselect_b32 s55, s45, s11
	v_mfma_f32_16x16x32_bf16 v[42:45], v[190:193], v[226:229], v[42:45]
	s_cselect_b32 s54, s90, s10
	v_mfma_f32_16x16x32_bf16 v[30:33], v[170:173], v[234:237], v[30:33]
	v_add_u32_e32 v130, s12, v163
	v_mfma_f32_16x16x32_bf16 v[26:29], v[190:193], v[234:237], v[26:29]
	s_cselect_b32 s53, s4, s94
	v_mfma_f32_16x16x32_bf16 v[14:17], v[170:173], v[242:245], v[14:17]
	s_cselect_b32 s52, s43, s91
	v_mfma_f32_16x16x32_bf16 v[10:13], v[190:193], v[242:245], v[10:13]
	s_add_i32 s13, 0, 0x14000
	s_setprio 0
	s_setprio 1
	v_mfma_f32_16x16x32_bf16 v[54:57], v[198:201], v[214:217], v[54:57]
	s_cmp_gt_u32 s95, 13
	v_mfma_f32_16x16x32_bf16 v[50:53], v[206:209], v[214:217], v[50:53]
	v_mfma_f32_16x16x32_bf16 v[38:41], v[198:201], v[222:225], v[38:41]
	v_mfma_f32_16x16x32_bf16 v[34:37], v[206:209], v[222:225], v[34:37]
	v_mfma_f32_16x16x32_bf16 v[22:25], v[198:201], v[230:233], v[22:25]
	v_mfma_f32_16x16x32_bf16 v[18:21], v[206:209], v[230:233], v[18:21]
	v_mfma_f32_16x16x32_bf16 v[6:9], v[198:201], v[238:241], v[6:9]
	v_mfma_f32_16x16x32_bf16 v[2:5], v[206:209], v[238:241], v[2:5]
	v_mfma_f32_16x16x32_bf16 v[54:57], v[202:205], v[218:221], v[54:57]
	v_mfma_f32_16x16x32_bf16 v[50:53], v[210:213], v[218:221], v[50:53]
	v_mfma_f32_16x16x32_bf16 v[38:41], v[202:205], v[226:229], v[38:41]
	v_mfma_f32_16x16x32_bf16 v[34:37], v[210:213], v[226:229], v[34:37]
	v_mfma_f32_16x16x32_bf16 v[22:25], v[202:205], v[234:237], v[22:25]
	v_mfma_f32_16x16x32_bf16 v[18:21], v[210:213], v[234:237], v[18:21]
	v_mfma_f32_16x16x32_bf16 v[6:9], v[202:205], v[242:245], v[6:9]
	v_mfma_f32_16x16x32_bf16 v[2:5], v[210:213], v[242:245], v[2:5]
	s_setprio 0
	s_barrier
	s_cbranch_scc0 .Lgk_603
	s_and_b64 vcc, exec, s[40:41]
	s_cbranch_vccz .LBB0_606
	s_barrier

; #define PG8_STAGE(bufoff, gbase, voff) do { _Pragma("unroll") for (int _i = 0; _i < 2; ++_i) \
;         __builtin_amdgcn_global_load_lds((const unsigned*)((const char*)(gbase) + (voff)[_i]), (PG8_LAS unsigned*)(lds + (bufoff) + ldsw + _i * 8192), 16, 0, 0); } while (0)
; #define PG8_LDA(dst, b, h) do { _Pragma("unroll") for (int m = 0; m < 4; ++m) _Pragma("unroll") for (int k = 0; k < 2; ++k) dst[m][k] = *(const PG8_LAS bf16x8*)(lds + PG8_SA(b, h) + aoff + m * 2048 + k * 1024); } while (0)
; #define PG8_LDB(dst, b, h) do { _Pragma("unroll") for (int n = 0; n < 2; ++n) _Pragma("unroll") for (int k = 0; k < 2; ++k) dst[n][k] = *(const PG8_LAS bf16x8*)(lds + PG8_SB(b, h) + boff + n * 2048 + k * 1024); } while (0)
; #define PG8_MMA(ai, bj, At, Bt) do { __builtin_amdgcn_s_setprio(1); _Pragma("unroll") for (int m = 0; m < 4; ++m) _Pragma("unroll") for (int n = 0; n < 2; ++n) _Pragma("unroll") for (int k = 0; k < 2; ++k) \
;         acc[ai][bj][m][n] = __builtin_amdgcn_mfma_f32_16x16x32_bf16(Bt[n][k], At[m][k], acc[ai][bj][m][n], 0, 0, 0); __builtin_amdgcn_s_setprio(0); } while (0)
; #define PG8_WAIT_V(n) asm volatile("s_waitcnt vmcnt(" #n ")" ::: "memory")
; #define PG8_WAIT_L(n) asm volatile("s_waitcnt lgkmcnt(" #n ")" ::: "memory")
; #define PG8_BAR __builtin_amdgcn_s_barrier()
; #define PG8_SCHED __builtin_amdgcn_sched_barrier(0)
; template <class Epi, class Sched, bool ALIGN_EPI = false, bool SP2 = false>
; __device__ __forceinline__ void gemm_phase(PG8_LAS unsigned char* lds, const Gemm g, const Sched& S, const Epi& E) {
;     ...
;             PG8_LDB(B0, 0, 0); PG8_LDB(B1, 0, 1); PG8_SCHED; PG8_LDA(At, 0, 0); PG8_STAGE(PG8_SA(1, 1), a1 + hstepA, voffA);
;             PG8_WAIT_V(8); PG8_WAIT_L(0); PG8_BAR; PG8_MMA(0, 0, At, B0); PG8_MMA(0, 1, At, B1); PG8_BAR; PG8_SCHED;
;             PG8_LDA(At, 0, 1); PG8_STAGE(PG8_SB(0, 0), b2, voffB); PG8_STAGE(PG8_SB(0, 1), b2 + hstepB, voffB); PG8_STAGE(PG8_SA(0, 0), a2, voffA);
;             PG8_WAIT_V(8); PG8_WAIT_L(0); PG8_BAR; PG8_MMA(1, 0, At, B0); PG8_MMA(1, 1, At, B1); PG8_BAR; PG8_SCHED;
.Lgk_623:
	ds_read_b128 v[160:163], v130
	ds_read_b128 v[164:167], v130 offset:1024
	ds_read_b128 v[186:189], v130 offset:2048
	ds_read_b128 v[190:193], v130 offset:3072
	v_add_u32_e32 v130, s13, v169
	ds_read_b128 v[198:201], v130
	ds_read_b128 v[202:205], v130 offset:1024
	ds_read_b128 v[206:209], v130 offset:2048
	ds_read_b128 v[210:213], v130 offset:3072
	v_lshl_add_u64 v[130:131], s[54:55], 0, v[156:157]
	s_add_i32 m0, s53, 0xc000
	ds_read_b128 v[214:217], v171
	ds_read_b128 v[218:221], v171 offset:1024
	ds_read_b128 v[222:225], v171 offset:2048
	ds_read_b128 v[226:229], v171 offset:3072
	ds_read_b128 v[230:233], v171 offset:4096
	ds_read_b128 v[234:237], v171 offset:5120
	ds_read_b128 v[238:241], v171 offset:6144
	ds_read_b128 v[242:245], v171 offset:7168
	global_load_lds_dwordx4 v[130:131], off
	v_lshl_add_u64 v[130:131], s[54:55], 0, v[158:159]
	s_add_i32 m0, s53, 0xe000
	s_nop 0
	global_load_lds_dwordx4 v[130:131], off
	s_waitcnt vmcnt(8)
	s_waitcnt lgkmcnt(0)
	s_barrier
	s_setprio 1
	s_waitcnt lgkmcnt(0)
	v_mfma_f32_16x16x32_bf16 v[126:129], v[160:163], v[214:217], v[126:129]
	v_mfma_f32_16x16x32_bf16 v[122:125], v[186:189], v[214:217], v[122:125]
	v_mfma_f32_16x16x32_bf16 v[110:113], v[160:163], v[222:225], v[110:113]
	v_mfma_f32_16x16x32_bf16 v[106:109], v[186:189], v[222:225], v[106:109]
	v_mfma_f32_16x16x32_bf16 v[94:97], v[160:163], v[230:233], v[94:97]
	v_mfma_f32_16x16x32_bf16 v[90:93], v[186:189], v[230:233], v[90:93]
	v_mfma_f32_16x16x32_bf16 v[78:81], v[160:163], v[238:241], v[78:81]
	v_mfma_f32_16x16x32_bf16 v[74:77], v[186:189], v[238:241], v[74:77]
	v_mfma_f32_16x16x32_bf16 v[126:129], v[164:167], v[218:221], v[126:129]
	v_mfma_f32_16x16x32_bf16 v[122:125], v[190:193], v[218:221], v[122:125]
	v_mfma_f32_16x16x32_bf16 v[110:113], v[164:167], v[226:229], v[110:113]
	v_mfma_f32_16x16x32_bf16 v[106:109], v[190:193], v[226:229], v[106:109]
	v_mfma_f32_16x16x32_bf16 v[94:97], v[164:167], v[234:237], v[94:97]
	v_mfma_f32_16x16x32_bf16 v[90:93], v[190:193], v[234:237], v[90:93]
	v_mfma_f32_16x16x32_bf16 v[78:81], v[164:167], v[242:245], v[78:81]
	v_mfma_f32_16x16x32_bf16 v[74:77], v[190:193], v[242:245], v[74:77]
	s_setprio 0
	s_setprio 1
	v_mfma_f32_16x16x32_bf16 v[118:121], v[198:201], v[214:217], v[118:121]
	v_mfma_f32_16x16x32_bf16 v[114:117], v[206:209], v[214:217], v[114:117]
	v_mfma_f32_16x16x32_bf16 v[102:105], v[198:201], v[222:225], v[102:105]
	v_mfma_f32_16x16x32_bf16 v[98:101], v[206:209], v[222:225], v[98:101]
	v_mfma_f32_16x16x32_bf16 v[86:89], v[198:201], v[230:233], v[86:89]
	v_mfma_f32_16x16x32_bf16 v[82:85], v[206:209], v[230:233], v[82:85]
	v_mfma_f32_16x16x32_bf16 v[70:73], v[198:201], v[238:241], v[70:73]
	v_mfma_f32_16x16x32_bf16 v[66:69], v[206:209], v[238:241], v[66:69]
	v_mfma_f32_16x16x32_bf16 v[118:121], v[202:205], v[218:221], v[118:121]
	v_mfma_f32_16x16x32_bf16 v[114:117], v[210:213], v[218:221], v[114:117]
	v_mfma_f32_16x16x32_bf16 v[102:105], v[202:205], v[226:229], v[102:105]
	v_mfma_f32_16x16x32_bf16 v[98:101], v[210:213], v[226:229], v[98:101]
	v_mfma_f32_16x16x32_bf16 v[86:89], v[202:205], v[234:237], v[86:89]
	v_mfma_f32_16x16x32_bf16 v[82:85], v[210:213], v[234:237], v[82:85]
	v_mfma_f32_16x16x32_bf16 v[70:73], v[202:205], v[242:245], v[70:73]
	v_mfma_f32_16x16x32_bf16 v[66:69], v[210:213], v[242:245], v[66:69]
	s_setprio 0
	s_barrier
	s_add_i32 s10, s12, s68
	v_lshl_add_u64 v[130:131], s[56:57], 0, v[0:1]
	s_mov_b32 m0, s10
	ds_read_b128 v[214:217], v171 offset:16384
	ds_read_b128 v[218:221], v171 offset:17408
	ds_read_b128 v[222:225], v171 offset:18432
	ds_read_b128 v[226:229], v171 offset:19456
	ds_read_b128 v[230:233], v171 offset:20480
	ds_read_b128 v[234:237], v171 offset:21504
	ds_read_b128 v[238:241], v171 offset:22528
	ds_read_b128 v[242:245], v171 offset:23552
	global_load_lds_dwordx4 v[130:131], off
	s_add_i32 m0, s10, 0x2000
	s_add_u32 s10, s56, 0x20000
	v_lshl_add_u64 v[132:133], s[56:57], 0, v[150:151]
	s_addc_u32 s11, s57, 0
	s_add_i32 s12, s13, s68
	global_load_lds_dwordx4 v[132:133], off
	v_lshl_add_u64 v[172:173], s[10:11], 0, v[0:1]
	s_mov_b32 m0, s12
	v_lshl_add_u64 v[246:247], s[62:63], 0, v[152:153]
	global_load_lds_dwordx4 v[172:173], off
	v_lshl_add_u64 v[172:173], s[10:11], 0, v[150:151]
	s_add_i32 m0, s12, 0x2000
	s_nop 0
	global_load_lds_dwordx4 v[172:173], off
	v_lshl_add_u64 v[172:173], s[62:63], 0, v[154:155]
	s_mov_b32 m0, s53
	s_nop 0
	global_load_lds_dwordx4 v[172:173], off
	s_mov_b32 m0, s69
	s_nop 0
	global_load_lds_dwordx4 v[246:247], off
	s_waitcnt vmcnt(8)
	s_waitcnt lgkmcnt(0)
	s_barrier
; #define PG8_STAGE(bufoff, gbase, voff) do { _Pragma("unroll") for (int _i = 0; _i < 2; ++_i) \
;         __builtin_amdgcn_global_load_lds((const unsigned*)((const char*)(gbase) + (voff)[_i]), (PG8_LAS unsigned*)(lds + (bufoff) + ldsw + _i * 8192), 16, 0, 0); } while (0)
; #define PG8_LDA(dst, b, h) do { _Pragma("unroll") for (int m = 0; m < 4; ++m) _Pragma("unroll") for (int k = 0; k < 2; ++k) dst[m][k] = *(const PG8_LAS bf16x8*)(lds + PG8_SA(b, h) + aoff + m * 2048 + k * 1024); } while (0)
; #define PG8_LDB(dst, b, h) do { _Pragma("unroll") for (int n = 0; n < 2; ++n) _Pragma("unroll") for (int k = 0; k < 2; ++k) dst[n][k] = *(const PG8_LAS bf16x8*)(lds + PG8_SB(b, h) + boff + n * 2048 + k * 1024); } while (0)
; #define PG8_MMA(ai, bj, At, Bt) do { __builtin_amdgcn_s_setprio(1); _Pragma("unroll") for (int m = 0; m < 4; ++m) _Pragma("unroll") for (int n = 0; n < 2; ++n) _Pragma("unroll") for (int k = 0; k < 2; ++k) \
;         acc[ai][bj][m][n] = __builtin_amdgcn_mfma_f32_16x16x32_bf16(Bt[n][k], At[m][k], acc[ai][bj][m][n], 0, 0, 0); __builtin_amdgcn_s_setprio(0); } while (0)
; #define PG8_WAIT_V(n) asm volatile("s_waitcnt vmcnt(" #n ")" ::: "memory")
; #define PG8_WAIT_L(n) asm volatile("s_waitcnt lgkmcnt(" #n ")" ::: "memory")
; #define PG8_BAR __builtin_amdgcn_s_barrier()
; #define PG8_SCHED __builtin_amdgcn_sched_barrier(0)
; template <class Epi, class Sched, bool ALIGN_EPI = false, bool SP2 = false>
; __device__ __forceinline__ void gemm_phase(PG8_LAS unsigned char* lds, const Gemm g, const Sched& S, const Epi& E) {
;     ...
;             PG8_WAIT_V(8); PG8_WAIT_L(0); PG8_BAR; PG8_MMA(1, 0, At, B0); PG8_MMA(1, 1, At, B1); PG8_BAR; PG8_SCHED;
;             PG8_LDB(B0, 1, 0); PG8_LDB(B1, 1, 1); PG8_SCHED; PG8_LDA(At, 1, 0); PG8_STAGE(PG8_SA(0, 1), a2 + hstepA, voffA);
;             PG8_WAIT_V(8); PG8_WAIT_L(0); PG8_BAR; PG8_MMA(0, 0, At, B0); PG8_MMA(0, 1, At, B1); PG8_BAR; PG8_SCHED;
	s_setprio 1
	s_waitcnt lgkmcnt(0)
	v_mfma_f32_16x16x32_bf16 v[62:65], v[160:163], v[214:217], v[62:65]
	v_mfma_f32_16x16x32_bf16 v[58:61], v[186:189], v[214:217], v[58:61]
	v_mfma_f32_16x16x32_bf16 v[46:49], v[160:163], v[222:225], v[46:49]
	v_mfma_f32_16x16x32_bf16 v[42:45], v[186:189], v[222:225], v[42:45]
	v_mfma_f32_16x16x32_bf16 v[30:33], v[160:163], v[230:233], v[30:33]
	v_mfma_f32_16x16x32_bf16 v[26:29], v[186:189], v[230:233], v[26:29]
	v_mfma_f32_16x16x32_bf16 v[14:17], v[160:163], v[238:241], v[14:17]
	v_mfma_f32_16x16x32_bf16 v[10:13], v[186:189], v[238:241], v[10:13]
	v_mfma_f32_16x16x32_bf16 v[62:65], v[164:167], v[218:221], v[62:65]
	v_mfma_f32_16x16x32_bf16 v[58:61], v[190:193], v[218:221], v[58:61]
	v_mfma_f32_16x16x32_bf16 v[46:49], v[164:167], v[226:229], v[46:49]
	v_mfma_f32_16x16x32_bf16 v[42:45], v[190:193], v[226:229], v[42:45]
	v_mfma_f32_16x16x32_bf16 v[30:33], v[164:167], v[234:237], v[30:33]
	v_mfma_f32_16x16x32_bf16 v[26:29], v[190:193], v[234:237], v[26:29]
	v_mfma_f32_16x16x32_bf16 v[14:17], v[164:167], v[242:245], v[14:17]
	v_mfma_f32_16x16x32_bf16 v[10:13], v[190:193], v[242:245], v[10:13]
	s_setprio 0
	s_setprio 1
	v_mfma_f32_16x16x32_bf16 v[54:57], v[198:201], v[214:217], v[54:57]
	v_mfma_f32_16x16x32_bf16 v[50:53], v[206:209], v[214:217], v[50:53]
	v_mfma_f32_16x16x32_bf16 v[38:41], v[198:201], v[222:225], v[38:41]
	v_mfma_f32_16x16x32_bf16 v[34:37], v[206:209], v[222:225], v[34:37]
	v_mfma_f32_16x16x32_bf16 v[22:25], v[198:201], v[230:233], v[22:25]
	v_mfma_f32_16x16x32_bf16 v[18:21], v[206:209], v[230:233], v[18:21]
	v_mfma_f32_16x16x32_bf16 v[6:9], v[198:201], v[238:241], v[6:9]
	v_mfma_f32_16x16x32_bf16 v[2:5], v[206:209], v[238:241], v[2:5]
	v_mfma_f32_16x16x32_bf16 v[54:57], v[202:205], v[218:221], v[54:57]
	v_mfma_f32_16x16x32_bf16 v[50:53], v[210:213], v[218:221], v[50:53]
	v_mfma_f32_16x16x32_bf16 v[38:41], v[202:205], v[226:229], v[38:41]
	v_mfma_f32_16x16x32_bf16 v[34:37], v[210:213], v[226:229], v[34:37]
	v_mfma_f32_16x16x32_bf16 v[22:25], v[202:205], v[234:237], v[22:25]
	v_mfma_f32_16x16x32_bf16 v[18:21], v[210:213], v[234:237], v[18:21]
	v_mfma_f32_16x16x32_bf16 v[6:9], v[202:205], v[242:245], v[6:9]
	v_mfma_f32_16x16x32_bf16 v[2:5], v[210:213], v[242:245], v[2:5]
	s_setprio 0
	s_barrier
	s_add_i32 s12, 0, 0x18000
	s_add_i32 s13, 0, 0x1c000
	v_add_u32_e32 v190, s12, v169
	v_add_u32_e32 v210, s13, v169
	ds_read_b128 v[160:163], v190
	ds_read_b128 v[164:167], v190 offset:1024
	ds_read_b128 v[186:189], v190 offset:2048
	ds_read_b128 v[190:193], v190 offset:3072
	ds_read_b128 v[198:201], v210
	ds_read_b128 v[202:205], v210 offset:1024
	ds_read_b128 v[206:209], v210 offset:2048
	ds_read_b128 v[210:213], v210 offset:3072
	s_add_u32 s10, s62, 0x20000
	s_addc_u32 s11, s63, 0
	s_mov_b32 m0, s94
	v_lshl_add_u64 v[248:249], s[10:11], 0, v[154:155]
	ds_read_b128 v[214:217], v171 offset:32768
	ds_read_b128 v[218:221], v171 offset:33792
	ds_read_b128 v[222:225], v171 offset:34816
	ds_read_b128 v[226:229], v171 offset:35840
	ds_read_b128 v[230:233], v171 offset:36864
	ds_read_b128 v[234:237], v171 offset:37888
	ds_read_b128 v[238:241], v171 offset:38912
	ds_read_b128 v[242:245], v171 offset:39936
	global_load_lds_dwordx4 v[248:249], off
	v_lshl_add_u64 v[248:249], s[10:11], 0, v[152:153]
	s_mov_b32 m0, s95
	s_nop 0
	global_load_lds_dwordx4 v[248:249], off
	s_waitcnt vmcnt(8)
	s_waitcnt lgkmcnt(0)
	s_barrier
	s_setprio 1
	s_waitcnt lgkmcnt(0)
	v_mfma_f32_16x16x32_bf16 v[126:129], v[160:163], v[214:217], v[126:129]
	v_mfma_f32_16x16x32_bf16 v[122:125], v[186:189], v[214:217], v[122:125]
	v_mfma_f32_16x16x32_bf16 v[110:113], v[160:163], v[222:225], v[110:113]
	v_mfma_f32_16x16x32_bf16 v[106:109], v[186:189], v[222:225], v[106:109]
	v_mfma_f32_16x16x32_bf16 v[94:97], v[160:163], v[230:233], v[94:97]
	v_mfma_f32_16x16x32_bf16 v[90:93], v[186:189], v[230:233], v[90:93]
	v_mfma_f32_16x16x32_bf16 v[78:81], v[160:163], v[238:241], v[78:81]
	v_mfma_f32_16x16x32_bf16 v[74:77], v[186:189], v[238:241], v[74:77]
	v_mfma_f32_16x16x32_bf16 v[126:129], v[164:167], v[218:221], v[126:129]
	v_mfma_f32_16x16x32_bf16 v[122:125], v[190:193], v[218:221], v[122:125]
	v_mfma_f32_16x16x32_bf16 v[110:113], v[164:167], v[226:229], v[110:113]
	v_mfma_f32_16x16x32_bf16 v[106:109], v[190:193], v[226:229], v[106:109]
	v_mfma_f32_16x16x32_bf16 v[94:97], v[164:167], v[234:237], v[94:97]
	v_mfma_f32_16x16x32_bf16 v[90:93], v[190:193], v[234:237], v[90:93]
	v_mfma_f32_16x16x32_bf16 v[78:81], v[164:167], v[242:245], v[78:81]
	v_mfma_f32_16x16x32_bf16 v[74:77], v[190:193], v[242:245], v[74:77]
	s_setprio 0
	s_setprio 1
	v_mfma_f32_16x16x32_bf16 v[118:121], v[198:201], v[214:217], v[118:121]
	v_mfma_f32_16x16x32_bf16 v[114:117], v[206:209], v[214:217], v[114:117]
	v_mfma_f32_16x16x32_bf16 v[102:105], v[198:201], v[222:225], v[102:105]
	v_mfma_f32_16x16x32_bf16 v[98:101], v[206:209], v[222:225], v[98:101]
	v_mfma_f32_16x16x32_bf16 v[86:89], v[198:201], v[230:233], v[86:89]
	v_mfma_f32_16x16x32_bf16 v[82:85], v[206:209], v[230:233], v[82:85]
	v_mfma_f32_16x16x32_bf16 v[70:73], v[198:201], v[238:241], v[70:73]
	v_mfma_f32_16x16x32_bf16 v[66:69], v[206:209], v[238:241], v[66:69]
	v_mfma_f32_16x16x32_bf16 v[118:121], v[202:205], v[218:221], v[118:121]
	v_mfma_f32_16x16x32_bf16 v[114:117], v[210:213], v[218:221], v[114:117]
	v_mfma_f32_16x16x32_bf16 v[102:105], v[202:205], v[226:229], v[102:105]
	v_mfma_f32_16x16x32_bf16 v[98:101], v[210:213], v[226:229], v[98:101]
	v_mfma_f32_16x16x32_bf16 v[86:89], v[202:205], v[234:237], v[86:89]
	v_mfma_f32_16x16x32_bf16 v[82:85], v[210:213], v[234:237], v[82:85]
	v_mfma_f32_16x16x32_bf16 v[70:73], v[202:205], v[242:245], v[70:73]
	v_mfma_f32_16x16x32_bf16 v[66:69], v[210:213], v[242:245], v[66:69]
	s_setprio 0
	s_barrier
; #define PG8_STAGE(bufoff, gbase, voff) do { _Pragma("unroll") for (int _i = 0; _i < 2; ++_i) \
;         __builtin_amdgcn_global_load_lds((const unsigned*)((const char*)(gbase) + (voff)[_i]), (PG8_LAS unsigned*)(lds + (bufoff) + ldsw + _i * 8192), 16, 0, 0); } while (0)
; #define PG8_LDA(dst, b, h) do { _Pragma("unroll") for (int m = 0; m < 4; ++m) _Pragma("unroll") for (int k = 0; k < 2; ++k) dst[m][k] = *(const PG8_LAS bf16x8*)(lds + PG8_SA(b, h) + aoff + m * 2048 + k * 1024); } while (0)
; #define PG8_LDB(dst, b, h) do { _Pragma("unroll") for (int n = 0; n < 2; ++n) _Pragma("unroll") for (int k = 0; k < 2; ++k) dst[n][k] = *(const PG8_LAS bf16x8*)(lds + PG8_SB(b, h) + boff + n * 2048 + k * 1024); } while (0)
; template <class Epi, class Sched, bool ALIGN_EPI = false, bool SP2 = false>
; __device__ __forceinline__ void gemm_phase(PG8_LAS unsigned char* lds, const Gemm g, const Sched& S, const Epi& E) {
;     ...
;         for (int t = 0; t < nt; t += 2) {
;             const bool last = (t == nt - 2);
;             const char* a1 = cA + (size_t)(t + 1) * kstep;
;             const char* a2 = last ? nA : cA + (size_t)(t + 2) * kstep; const char* b2 = last ? nB : cB + (size_t)(t + 2) * kstep;
;             const char* a3 = a2 + kstep; const char* b3 = b2 + kstep;
;             if (last && has_next) S.a_ready(nxt);
;             if constexpr (SP2) {
;             PG8_LDB(B0, 0, 0); PG8_LDB(B1, 0, 1); PG8_SCHED; PG8_LDA(At, 0, 0); PG8_STAGE(PG8_SA(1, 1), a1 + hstepA, voffA);
;             PG8_WAIT_V(8); PG8_WAIT_L(0); PG8_BAR; PG8_MMA(0, 0, At, B0); PG8_MMA(0, 1, At, B1); PG8_BAR; PG8_SCHED;
;             PG8_LDA(At, 0, 1); PG8_STAGE(PG8_SB(0, 0), b2, voffB); PG8_STAGE(PG8_SB(0, 1), b2 + hstepB, voffB); PG8_STAGE(PG8_SA(0, 0), a2, voffA);
;             PG8_WAIT_V(8); PG8_WAIT_L(0); PG8_BAR; PG8_MMA(1, 0, At, B0); PG8_MMA(1, 1, At, B1); PG8_BAR; PG8_SCHED;
;             PG8_LDB(B0, 1, 0); PG8_LDB(B1, 1, 1); PG8_SCHED; PG8_LDA(At, 1, 0); PG8_STAGE(PG8_SA(0, 1), a2 + hstepA, voffA);
;             PG8_WAIT_V(8); PG8_WAIT_L(0); PG8_BAR; PG8_MMA(0, 0, At, B0); PG8_MMA(0, 1, At, B1); PG8_BAR; PG8_SCHED;
;             PG8_LDA(At, 1, 1); PG8_STAGE(PG8_SB(1, 0), b3, voffB); PG8_STAGE(PG8_SB(1, 1), b3 + hstepB, voffB); PG8_STAGE(PG8_SA(1, 0), a3, voffA);
;             PG8_WAIT_V(8); PG8_WAIT_L(0); PG8_BAR; PG8_MMA(1, 0, At, B0); PG8_MMA(1, 1, At, B1); PG8_BAR; PG8_SCHED;
	s_add_i32 s10, s12, s68
	v_lshl_add_u64 v[130:131], v[130:131], 0, s[2:3]
	s_mov_b32 m0, s10
	ds_read_b128 v[214:217], v171 offset:49152
	ds_read_b128 v[218:221], v171 offset:50176
	ds_read_b128 v[222:225], v171 offset:51200
	ds_read_b128 v[226:229], v171 offset:52224
	ds_read_b128 v[230:233], v171 offset:53248
	ds_read_b128 v[234:237], v171 offset:54272
	ds_read_b128 v[238:241], v171 offset:55296
	ds_read_b128 v[242:245], v171 offset:56320
	global_load_lds_dwordx4 v[130:131], off
	s_add_i32 m0, s10, 0x2000
	s_add_u32 s10, s56, 0x20080
	v_lshl_add_u64 v[130:131], v[132:133], 0, s[2:3]
	s_addc_u32 s11, s57, 0
	s_add_i32 s12, s13, s68
	global_load_lds_dwordx4 v[130:131], off
	v_lshl_add_u64 v[130:131], s[10:11], 0, v[0:1]
	s_mov_b32 m0, s12
	s_nop 0
	global_load_lds_dwordx4 v[130:131], off
	v_lshl_add_u64 v[130:131], s[10:11], 0, v[150:151]
	s_add_i32 m0, s12, 0x2000
	s_nop 0
	global_load_lds_dwordx4 v[130:131], off
	v_lshl_add_u64 v[130:131], v[172:173], 0, s[2:3]
	s_mov_b32 m0, s8
	s_nop 0
	global_load_lds_dwordx4 v[130:131], off
	v_lshl_add_u64 v[130:131], v[246:247], 0, s[2:3]
	s_mov_b32 m0, s9
	s_nop 0
	global_load_lds_dwordx4 v[130:131], off
	s_waitcnt vmcnt(8)
	s_waitcnt lgkmcnt(0)
	s_barrier
	s_setprio 1
	s_waitcnt lgkmcnt(0)
	v_mfma_f32_16x16x32_bf16 v[62:65], v[160:163], v[214:217], v[62:65]
	v_mfma_f32_16x16x32_bf16 v[58:61], v[186:189], v[214:217], v[58:61]
	s_add_i32 vcc_hi, vcc_hi, 2
	v_mfma_f32_16x16x32_bf16 v[46:49], v[160:163], v[222:225], v[46:49]
	s_add_u32 s54, s54, 0x100
	v_mfma_f32_16x16x32_bf16 v[42:45], v[186:189], v[222:225], v[42:45]
	s_addc_u32 s55, s55, 0
	v_mfma_f32_16x16x32_bf16 v[30:33], v[160:163], v[230:233], v[30:33]
	s_add_u32 s91, s91, 0x100
	v_mfma_f32_16x16x32_bf16 v[26:29], v[186:189], v[230:233], v[26:29]
	s_addc_u32 vcc_lo, vcc_lo, 0
	v_mfma_f32_16x16x32_bf16 v[14:17], v[160:163], v[238:241], v[14:17]
	s_add_u32 s10, s54, 0xfffe0080
	v_mfma_f32_16x16x32_bf16 v[10:13], v[186:189], v[238:241], v[10:13]
	s_addc_u32 s11, s55, -1
	v_mfma_f32_16x16x32_bf16 v[62:65], v[164:167], v[218:221], v[62:65]
	s_add_i32 s12, 0, 0x10000
	v_mfma_f32_16x16x32_bf16 v[58:61], v[190:193], v[218:221], v[58:61]
	s_cmp_eq_u32 vcc_hi, 4
	v_mfma_f32_16x16x32_bf16 v[46:49], v[164:167], v[226:229], v[46:49]
	s_cselect_b32 s63, s41, s11
	v_mfma_f32_16x16x32_bf16 v[42:45], v[190:193], v[226:229], v[42:45]
	s_cselect_b32 s62, s47, s10
	v_mfma_f32_16x16x32_bf16 v[30:33], v[164:167], v[234:237], v[30:33]
	v_add_u32_e32 v130, s12, v169
	v_mfma_f32_16x16x32_bf16 v[26:29], v[190:193], v[234:237], v[26:29]
	s_cselect_b32 s57, s4, vcc_lo
	v_mfma_f32_16x16x32_bf16 v[14:17], v[164:167], v[242:245], v[14:17]
	s_cselect_b32 s56, s45, s91
	v_mfma_f32_16x16x32_bf16 v[10:13], v[190:193], v[242:245], v[10:13]
	s_add_i32 s13, 0, 0x14000
	s_setprio 0
	s_setprio 1
	v_mfma_f32_16x16x32_bf16 v[54:57], v[198:201], v[214:217], v[54:57]
	s_cmp_gt_u32 vcc_hi, 5
	v_mfma_f32_16x16x32_bf16 v[50:53], v[206:209], v[214:217], v[50:53]
	v_mfma_f32_16x16x32_bf16 v[38:41], v[198:201], v[222:225], v[38:41]
	v_mfma_f32_16x16x32_bf16 v[34:37], v[206:209], v[222:225], v[34:37]
	v_mfma_f32_16x16x32_bf16 v[22:25], v[198:201], v[230:233], v[22:25]
	v_mfma_f32_16x16x32_bf16 v[18:21], v[206:209], v[230:233], v[18:21]
	v_mfma_f32_16x16x32_bf16 v[6:9], v[198:201], v[238:241], v[6:9]
	v_mfma_f32_16x16x32_bf16 v[2:5], v[206:209], v[238:241], v[2:5]
	v_mfma_f32_16x16x32_bf16 v[54:57], v[202:205], v[218:221], v[54:57]
	v_mfma_f32_16x16x32_bf16 v[50:53], v[210:213], v[218:221], v[50:53]
	v_mfma_f32_16x16x32_bf16 v[38:41], v[202:205], v[226:229], v[38:41]
	v_mfma_f32_16x16x32_bf16 v[34:37], v[210:213], v[226:229], v[34:37]
	v_mfma_f32_16x16x32_bf16 v[22:25], v[202:205], v[234:237], v[22:25]
	v_mfma_f32_16x16x32_bf16 v[18:21], v[210:213], v[234:237], v[18:21]
	v_mfma_f32_16x16x32_bf16 v[6:9], v[202:205], v[242:245], v[6:9]
	v_mfma_f32_16x16x32_bf16 v[2:5], v[210:213], v[242:245], v[2:5]
	s_setprio 0
	s_barrier
	s_cbranch_scc0 .Lgk_623
	s_and_b64 vcc, exec, s[42:43]
	s_cbranch_vccz .LBB0_626
	s_barrier

; #define PG8_STAGE(bufoff, gbase, voff) do { _Pragma("unroll") for (int _i = 0; _i < 2; ++_i) \
;         __builtin_amdgcn_global_load_lds((const unsigned*)((const char*)(gbase) + (voff)[_i]), (PG8_LAS unsigned*)(lds + (bufoff) + ldsw + _i * 8192), 16, 0, 0); } while (0)
; #define PG8_LDA(dst, b, h) do { _Pragma("unroll") for (int m = 0; m < 4; ++m) _Pragma("unroll") for (int k = 0; k < 2; ++k) dst[m][k] = *(const PG8_LAS bf16x8*)(lds + PG8_SA(b, h) + aoff + m * 2048 + k * 1024); } while (0)
; #define PG8_LDB(dst, b, h) do { _Pragma("unroll") for (int n = 0; n < 2; ++n) _Pragma("unroll") for (int k = 0; k < 2; ++k) dst[n][k] = *(const PG8_LAS bf16x8*)(lds + PG8_SB(b, h) + boff + n * 2048 + k * 1024); } while (0)
; #define PG8_MMA(ai, bj, At, Bt) do { __builtin_amdgcn_s_setprio(1); _Pragma("unroll") for (int m = 0; m < 4; ++m) _Pragma("unroll") for (int n = 0; n < 2; ++n) _Pragma("unroll") for (int k = 0; k < 2; ++k) \
;         acc[ai][bj][m][n] = __builtin_amdgcn_mfma_f32_16x16x32_bf16(Bt[n][k], At[m][k], acc[ai][bj][m][n], 0, 0, 0); __builtin_amdgcn_s_setprio(0); } while (0)
; #define PG8_WAIT_V(n) asm volatile("s_waitcnt vmcnt(" #n ")" ::: "memory")
; #define PG8_WAIT_L(n) asm volatile("s_waitcnt lgkmcnt(" #n ")" ::: "memory")
; #define PG8_BAR __builtin_amdgcn_s_barrier()
; #define PG8_SCHED __builtin_amdgcn_sched_barrier(0)
; template <class Epi, class Sched, bool ALIGN_EPI = false, bool SP2 = false>
; __device__ __forceinline__ void gemm_phase(PG8_LAS unsigned char* lds, const Gemm g, const Sched& S, const Epi& E) {
;     ...
;             PG8_LDB(B0, 0, 0); PG8_LDB(B1, 0, 1); PG8_SCHED; PG8_LDA(At, 0, 0); PG8_STAGE(PG8_SA(1, 1), a1 + hstepA, voffA);
;             PG8_WAIT_V(8); PG8_WAIT_L(0); PG8_BAR; PG8_MMA(0, 0, At, B0); PG8_MMA(0, 1, At, B1); PG8_BAR; PG8_SCHED;
;             PG8_LDA(At, 0, 1); PG8_STAGE(PG8_SB(0, 0), b2, voffB); PG8_STAGE(PG8_SB(0, 1), b2 + hstepB, voffB); PG8_STAGE(PG8_SA(0, 0), a2, voffA);
;             PG8_WAIT_V(8); PG8_WAIT_L(0); PG8_BAR; PG8_MMA(1, 0, At, B0); PG8_MMA(1, 1, At, B1); PG8_BAR; PG8_SCHED;
.Lgk_929:
	ds_read_b128 v[160:163], v130
	ds_read_b128 v[170:173], v130 offset:1024
	ds_read_b128 v[186:189], v130 offset:2048
	ds_read_b128 v[190:193], v130 offset:3072
	v_add_u32_e32 v130, s13, v167
	ds_read_b128 v[198:201], v130
	ds_read_b128 v[202:205], v130 offset:1024
	ds_read_b128 v[206:209], v130 offset:2048
	ds_read_b128 v[210:213], v130 offset:3072
	v_lshl_add_u64 v[130:131], s[46:47], 0, v[156:157]
	s_add_i32 m0, s9, 0xc000
	ds_read_b128 v[214:217], v169
	ds_read_b128 v[218:221], v169 offset:1024
	ds_read_b128 v[222:225], v169 offset:2048
	ds_read_b128 v[226:229], v169 offset:3072
	ds_read_b128 v[230:233], v169 offset:4096
	ds_read_b128 v[234:237], v169 offset:5120
	ds_read_b128 v[238:241], v169 offset:6144
	ds_read_b128 v[242:245], v169 offset:7168
	global_load_lds_dwordx4 v[130:131], off
	v_lshl_add_u64 v[130:131], s[46:47], 0, v[158:159]
	s_add_i32 m0, s9, 0xe000
	s_nop 0
	global_load_lds_dwordx4 v[130:131], off
	s_waitcnt vmcnt(8)
	s_waitcnt lgkmcnt(0)
	s_barrier
	s_setprio 1
	s_waitcnt lgkmcnt(0)
	v_mfma_f32_16x16x32_bf16 v[126:129], v[160:163], v[214:217], v[126:129]
	v_mfma_f32_16x16x32_bf16 v[122:125], v[186:189], v[214:217], v[122:125]
	v_mfma_f32_16x16x32_bf16 v[110:113], v[160:163], v[222:225], v[110:113]
	v_mfma_f32_16x16x32_bf16 v[106:109], v[186:189], v[222:225], v[106:109]
	v_mfma_f32_16x16x32_bf16 v[94:97], v[160:163], v[230:233], v[94:97]
	v_mfma_f32_16x16x32_bf16 v[90:93], v[186:189], v[230:233], v[90:93]
	v_mfma_f32_16x16x32_bf16 v[78:81], v[160:163], v[238:241], v[78:81]
	v_mfma_f32_16x16x32_bf16 v[74:77], v[186:189], v[238:241], v[74:77]
	v_mfma_f32_16x16x32_bf16 v[126:129], v[170:173], v[218:221], v[126:129]
	v_mfma_f32_16x16x32_bf16 v[122:125], v[190:193], v[218:221], v[122:125]
	v_mfma_f32_16x16x32_bf16 v[110:113], v[170:173], v[226:229], v[110:113]
	v_mfma_f32_16x16x32_bf16 v[106:109], v[190:193], v[226:229], v[106:109]
	v_mfma_f32_16x16x32_bf16 v[94:97], v[170:173], v[234:237], v[94:97]
	v_mfma_f32_16x16x32_bf16 v[90:93], v[190:193], v[234:237], v[90:93]
	v_mfma_f32_16x16x32_bf16 v[78:81], v[170:173], v[242:245], v[78:81]
	v_mfma_f32_16x16x32_bf16 v[74:77], v[190:193], v[242:245], v[74:77]
	s_setprio 0
	s_setprio 1
	v_mfma_f32_16x16x32_bf16 v[118:121], v[198:201], v[214:217], v[118:121]
	v_mfma_f32_16x16x32_bf16 v[114:117], v[206:209], v[214:217], v[114:117]
	v_mfma_f32_16x16x32_bf16 v[102:105], v[198:201], v[222:225], v[102:105]
	v_mfma_f32_16x16x32_bf16 v[98:101], v[206:209], v[222:225], v[98:101]
	v_mfma_f32_16x16x32_bf16 v[86:89], v[198:201], v[230:233], v[86:89]
	v_mfma_f32_16x16x32_bf16 v[82:85], v[206:209], v[230:233], v[82:85]
	v_mfma_f32_16x16x32_bf16 v[70:73], v[198:201], v[238:241], v[70:73]
	v_mfma_f32_16x16x32_bf16 v[66:69], v[206:209], v[238:241], v[66:69]
	v_mfma_f32_16x16x32_bf16 v[118:121], v[202:205], v[218:221], v[118:121]
	v_mfma_f32_16x16x32_bf16 v[114:117], v[210:213], v[218:221], v[114:117]
	v_mfma_f32_16x16x32_bf16 v[102:105], v[202:205], v[226:229], v[102:105]
	v_mfma_f32_16x16x32_bf16 v[98:101], v[210:213], v[226:229], v[98:101]
	v_mfma_f32_16x16x32_bf16 v[86:89], v[202:205], v[234:237], v[86:89]
	v_mfma_f32_16x16x32_bf16 v[82:85], v[210:213], v[234:237], v[82:85]
	v_mfma_f32_16x16x32_bf16 v[70:73], v[202:205], v[242:245], v[70:73]
	v_mfma_f32_16x16x32_bf16 v[66:69], v[210:213], v[242:245], v[66:69]
	s_setprio 0
	s_barrier
	s_add_i32 s10, s12, s8
	v_lshl_add_u64 v[130:131], s[48:49], 0, v[0:1]
	s_mov_b32 m0, s10
	ds_read_b128 v[214:217], v169 offset:16384
	ds_read_b128 v[218:221], v169 offset:17408
	ds_read_b128 v[222:225], v169 offset:18432
	ds_read_b128 v[226:229], v169 offset:19456
	ds_read_b128 v[230:233], v169 offset:20480
	ds_read_b128 v[234:237], v169 offset:21504
	ds_read_b128 v[238:241], v169 offset:22528
	ds_read_b128 v[242:245], v169 offset:23552
	global_load_lds_dwordx4 v[130:131], off
	s_add_i32 m0, s10, 0x2000
	s_add_u32 s10, s48, 0x100000
	v_lshl_add_u64 v[132:133], s[48:49], 0, v[150:151]
	s_addc_u32 s11, s49, 0
	s_add_i32 s12, s13, s8
	global_load_lds_dwordx4 v[132:133], off
	v_lshl_add_u64 v[164:165], s[10:11], 0, v[0:1]
	s_mov_b32 m0, s12
	v_lshl_add_u64 v[246:247], s[50:51], 0, v[152:153]
	global_load_lds_dwordx4 v[164:165], off
	v_lshl_add_u64 v[164:165], s[10:11], 0, v[150:151]
	s_add_i32 m0, s12, 0x2000
	s_nop 0
	global_load_lds_dwordx4 v[164:165], off
	v_lshl_add_u64 v[164:165], s[50:51], 0, v[154:155]
	s_mov_b32 m0, s9
	s_nop 0
	global_load_lds_dwordx4 v[164:165], off
	s_mov_b32 m0, s30
	s_nop 0
	global_load_lds_dwordx4 v[246:247], off
	s_waitcnt vmcnt(8)
	s_waitcnt lgkmcnt(0)
	s_barrier
; #define PG8_STAGE(bufoff, gbase, voff) do { _Pragma("unroll") for (int _i = 0; _i < 2; ++_i) \
;         __builtin_amdgcn_global_load_lds((const unsigned*)((const char*)(gbase) + (voff)[_i]), (PG8_LAS unsigned*)(lds + (bufoff) + ldsw + _i * 8192), 16, 0, 0); } while (0)
; #define PG8_LDA(dst, b, h) do { _Pragma("unroll") for (int m = 0; m < 4; ++m) _Pragma("unroll") for (int k = 0; k < 2; ++k) dst[m][k] = *(const PG8_LAS bf16x8*)(lds + PG8_SA(b, h) + aoff + m * 2048 + k * 1024); } while (0)
; #define PG8_LDB(dst, b, h) do { _Pragma("unroll") for (int n = 0; n < 2; ++n) _Pragma("unroll") for (int k = 0; k < 2; ++k) dst[n][k] = *(const PG8_LAS bf16x8*)(lds + PG8_SB(b, h) + boff + n * 2048 + k * 1024); } while (0)
; #define PG8_MMA(ai, bj, At, Bt) do { __builtin_amdgcn_s_setprio(1); _Pragma("unroll") for (int m = 0; m < 4; ++m) _Pragma("unroll") for (int n = 0; n < 2; ++n) _Pragma("unroll") for (int k = 0; k < 2; ++k) \
;         acc[ai][bj][m][n] = __builtin_amdgcn_mfma_f32_16x16x32_bf16(Bt[n][k], At[m][k], acc[ai][bj][m][n], 0, 0, 0); __builtin_amdgcn_s_setprio(0); } while (0)
; #define PG8_WAIT_V(n) asm volatile("s_waitcnt vmcnt(" #n ")" ::: "memory")
; #define PG8_WAIT_L(n) asm volatile("s_waitcnt lgkmcnt(" #n ")" ::: "memory")
; #define PG8_BAR __builtin_amdgcn_s_barrier()
; #define PG8_SCHED __builtin_amdgcn_sched_barrier(0)
; template <class Epi, class Sched, bool ALIGN_EPI = false, bool SP2 = false>
; __device__ __forceinline__ void gemm_phase(PG8_LAS unsigned char* lds, const Gemm g, const Sched& S, const Epi& E) {
;     ...
;             PG8_WAIT_V(8); PG8_WAIT_L(0); PG8_BAR; PG8_MMA(1, 0, At, B0); PG8_MMA(1, 1, At, B1); PG8_BAR; PG8_SCHED;
;             PG8_LDB(B0, 1, 0); PG8_LDB(B1, 1, 1); PG8_SCHED; PG8_LDA(At, 1, 0); PG8_STAGE(PG8_SA(0, 1), a2 + hstepA, voffA);
;             PG8_WAIT_V(8); PG8_WAIT_L(0); PG8_BAR; PG8_MMA(0, 0, At, B0); PG8_MMA(0, 1, At, B1); PG8_BAR; PG8_SCHED;
	s_setprio 1
	s_waitcnt lgkmcnt(0)
	v_mfma_f32_16x16x32_bf16 v[62:65], v[160:163], v[214:217], v[62:65]
	v_mfma_f32_16x16x32_bf16 v[58:61], v[186:189], v[214:217], v[58:61]
	v_mfma_f32_16x16x32_bf16 v[46:49], v[160:163], v[222:225], v[46:49]
	v_mfma_f32_16x16x32_bf16 v[42:45], v[186:189], v[222:225], v[42:45]
	v_mfma_f32_16x16x32_bf16 v[30:33], v[160:163], v[230:233], v[30:33]
	v_mfma_f32_16x16x32_bf16 v[26:29], v[186:189], v[230:233], v[26:29]
	v_mfma_f32_16x16x32_bf16 v[14:17], v[160:163], v[238:241], v[14:17]
	v_mfma_f32_16x16x32_bf16 v[10:13], v[186:189], v[238:241], v[10:13]
	v_mfma_f32_16x16x32_bf16 v[62:65], v[170:173], v[218:221], v[62:65]
	v_mfma_f32_16x16x32_bf16 v[58:61], v[190:193], v[218:221], v[58:61]
	v_mfma_f32_16x16x32_bf16 v[46:49], v[170:173], v[226:229], v[46:49]
	v_mfma_f32_16x16x32_bf16 v[42:45], v[190:193], v[226:229], v[42:45]
	v_mfma_f32_16x16x32_bf16 v[30:33], v[170:173], v[234:237], v[30:33]
	v_mfma_f32_16x16x32_bf16 v[26:29], v[190:193], v[234:237], v[26:29]
	v_mfma_f32_16x16x32_bf16 v[14:17], v[170:173], v[242:245], v[14:17]
	v_mfma_f32_16x16x32_bf16 v[10:13], v[190:193], v[242:245], v[10:13]
	s_setprio 0
	s_setprio 1
	v_mfma_f32_16x16x32_bf16 v[54:57], v[198:201], v[214:217], v[54:57]
	v_mfma_f32_16x16x32_bf16 v[50:53], v[206:209], v[214:217], v[50:53]
	v_mfma_f32_16x16x32_bf16 v[38:41], v[198:201], v[222:225], v[38:41]
	v_mfma_f32_16x16x32_bf16 v[34:37], v[206:209], v[222:225], v[34:37]
	v_mfma_f32_16x16x32_bf16 v[22:25], v[198:201], v[230:233], v[22:25]
	v_mfma_f32_16x16x32_bf16 v[18:21], v[206:209], v[230:233], v[18:21]
	v_mfma_f32_16x16x32_bf16 v[6:9], v[198:201], v[238:241], v[6:9]
	v_mfma_f32_16x16x32_bf16 v[2:5], v[206:209], v[238:241], v[2:5]
	v_mfma_f32_16x16x32_bf16 v[54:57], v[202:205], v[218:221], v[54:57]
	v_mfma_f32_16x16x32_bf16 v[50:53], v[210:213], v[218:221], v[50:53]
	v_mfma_f32_16x16x32_bf16 v[38:41], v[202:205], v[226:229], v[38:41]
	v_mfma_f32_16x16x32_bf16 v[34:37], v[210:213], v[226:229], v[34:37]
	v_mfma_f32_16x16x32_bf16 v[22:25], v[202:205], v[234:237], v[22:25]
	v_mfma_f32_16x16x32_bf16 v[18:21], v[210:213], v[234:237], v[18:21]
	v_mfma_f32_16x16x32_bf16 v[6:9], v[202:205], v[242:245], v[6:9]
	v_mfma_f32_16x16x32_bf16 v[2:5], v[210:213], v[242:245], v[2:5]
	s_setprio 0
	s_barrier
	s_add_i32 s12, 0, 0x18000
	s_add_i32 s13, 0, 0x1c000
	v_add_u32_e32 v190, s12, v167
	v_add_u32_e32 v210, s13, v167
	ds_read_b128 v[160:163], v190
	ds_read_b128 v[170:173], v190 offset:1024
	ds_read_b128 v[186:189], v190 offset:2048
	ds_read_b128 v[190:193], v190 offset:3072
	ds_read_b128 v[198:201], v210
	ds_read_b128 v[202:205], v210 offset:1024
	ds_read_b128 v[206:209], v210 offset:2048
	ds_read_b128 v[210:213], v210 offset:3072
	s_add_u32 s10, s50, 0x100000
	s_addc_u32 s11, s51, 0
	s_mov_b32 m0, s31
	v_lshl_add_u64 v[248:249], s[10:11], 0, v[154:155]
	ds_read_b128 v[214:217], v169 offset:32768
	ds_read_b128 v[218:221], v169 offset:33792
	ds_read_b128 v[222:225], v169 offset:34816
	ds_read_b128 v[226:229], v169 offset:35840
	ds_read_b128 v[230:233], v169 offset:36864
	ds_read_b128 v[234:237], v169 offset:37888
	ds_read_b128 v[238:241], v169 offset:38912
	ds_read_b128 v[242:245], v169 offset:39936
	global_load_lds_dwordx4 v[248:249], off
	v_lshl_add_u64 v[248:249], s[10:11], 0, v[152:153]
	s_mov_b32 m0, s34
	s_nop 0
	global_load_lds_dwordx4 v[248:249], off
	s_waitcnt vmcnt(8)
	s_waitcnt lgkmcnt(0)
	s_barrier
	s_setprio 1
	s_waitcnt lgkmcnt(0)
	v_mfma_f32_16x16x32_bf16 v[126:129], v[160:163], v[214:217], v[126:129]
	v_mfma_f32_16x16x32_bf16 v[122:125], v[186:189], v[214:217], v[122:125]
	v_mfma_f32_16x16x32_bf16 v[110:113], v[160:163], v[222:225], v[110:113]
	v_mfma_f32_16x16x32_bf16 v[106:109], v[186:189], v[222:225], v[106:109]
	v_mfma_f32_16x16x32_bf16 v[94:97], v[160:163], v[230:233], v[94:97]
	v_mfma_f32_16x16x32_bf16 v[90:93], v[186:189], v[230:233], v[90:93]
	v_mfma_f32_16x16x32_bf16 v[78:81], v[160:163], v[238:241], v[78:81]
	v_mfma_f32_16x16x32_bf16 v[74:77], v[186:189], v[238:241], v[74:77]
	v_mfma_f32_16x16x32_bf16 v[126:129], v[170:173], v[218:221], v[126:129]
	v_mfma_f32_16x16x32_bf16 v[122:125], v[190:193], v[218:221], v[122:125]
	v_mfma_f32_16x16x32_bf16 v[110:113], v[170:173], v[226:229], v[110:113]
	v_mfma_f32_16x16x32_bf16 v[106:109], v[190:193], v[226:229], v[106:109]
	v_mfma_f32_16x16x32_bf16 v[94:97], v[170:173], v[234:237], v[94:97]
	v_mfma_f32_16x16x32_bf16 v[90:93], v[190:193], v[234:237], v[90:93]
	v_mfma_f32_16x16x32_bf16 v[78:81], v[170:173], v[242:245], v[78:81]
	v_mfma_f32_16x16x32_bf16 v[74:77], v[190:193], v[242:245], v[74:77]
	s_setprio 0
	s_setprio 1
	v_mfma_f32_16x16x32_bf16 v[118:121], v[198:201], v[214:217], v[118:121]
	v_mfma_f32_16x16x32_bf16 v[114:117], v[206:209], v[214:217], v[114:117]
	v_mfma_f32_16x16x32_bf16 v[102:105], v[198:201], v[222:225], v[102:105]
	v_mfma_f32_16x16x32_bf16 v[98:101], v[206:209], v[222:225], v[98:101]
	v_mfma_f32_16x16x32_bf16 v[86:89], v[198:201], v[230:233], v[86:89]
	v_mfma_f32_16x16x32_bf16 v[82:85], v[206:209], v[230:233], v[82:85]
	v_mfma_f32_16x16x32_bf16 v[70:73], v[198:201], v[238:241], v[70:73]
	v_mfma_f32_16x16x32_bf16 v[66:69], v[206:209], v[238:241], v[66:69]
	v_mfma_f32_16x16x32_bf16 v[118:121], v[202:205], v[218:221], v[118:121]
	v_mfma_f32_16x16x32_bf16 v[114:117], v[210:213], v[218:221], v[114:117]
	v_mfma_f32_16x16x32_bf16 v[102:105], v[202:205], v[226:229], v[102:105]
	v_mfma_f32_16x16x32_bf16 v[98:101], v[210:213], v[226:229], v[98:101]
	v_mfma_f32_16x16x32_bf16 v[86:89], v[202:205], v[234:237], v[86:89]
	v_mfma_f32_16x16x32_bf16 v[82:85], v[210:213], v[234:237], v[82:85]
	v_mfma_f32_16x16x32_bf16 v[70:73], v[202:205], v[242:245], v[70:73]
	v_mfma_f32_16x16x32_bf16 v[66:69], v[210:213], v[242:245], v[66:69]
	s_setprio 0
	s_barrier
; #define PG8_STAGE(bufoff, gbase, voff) do { _Pragma("unroll") for (int _i = 0; _i < 2; ++_i) \
;         __builtin_amdgcn_global_load_lds((const unsigned*)((const char*)(gbase) + (voff)[_i]), (PG8_LAS unsigned*)(lds + (bufoff) + ldsw + _i * 8192), 16, 0, 0); } while (0)
; #define PG8_LDA(dst, b, h) do { _Pragma("unroll") for (int m = 0; m < 4; ++m) _Pragma("unroll") for (int k = 0; k < 2; ++k) dst[m][k] = *(const PG8_LAS bf16x8*)(lds + PG8_SA(b, h) + aoff + m * 2048 + k * 1024); } while (0)
; #define PG8_LDB(dst, b, h) do { _Pragma("unroll") for (int n = 0; n < 2; ++n) _Pragma("unroll") for (int k = 0; k < 2; ++k) dst[n][k] = *(const PG8_LAS bf16x8*)(lds + PG8_SB(b, h) + boff + n * 2048 + k * 1024); } while (0)
; template <class Epi, class Sched, bool ALIGN_EPI = false, bool SP2 = false>
; __device__ __forceinline__ void gemm_phase(PG8_LAS unsigned char* lds, const Gemm g, const Sched& S, const Epi& E) {
;     ...
;         for (int t = 0; t < nt; t += 2) {
;             const bool last = (t == nt - 2);
;             const char* a1 = cA + (size_t)(t + 1) * kstep;
;             const char* a2 = last ? nA : cA + (size_t)(t + 2) * kstep; const char* b2 = last ? nB : cB + (size_t)(t + 2) * kstep;
;             const char* a3 = a2 + kstep; const char* b3 = b2 + kstep;
;             if (last && has_next) S.a_ready(nxt);
;             if constexpr (SP2) {
;             PG8_LDB(B0, 0, 0); PG8_LDB(B1, 0, 1); PG8_SCHED; PG8_LDA(At, 0, 0); PG8_STAGE(PG8_SA(1, 1), a1 + hstepA, voffA);
;             PG8_WAIT_V(8); PG8_WAIT_L(0); PG8_BAR; PG8_MMA(0, 0, At, B0); PG8_MMA(0, 1, At, B1); PG8_BAR; PG8_SCHED;
;             PG8_LDA(At, 0, 1); PG8_STAGE(PG8_SB(0, 0), b2, voffB); PG8_STAGE(PG8_SB(0, 1), b2 + hstepB, voffB); PG8_STAGE(PG8_SA(0, 0), a2, voffA);
;             PG8_WAIT_V(8); PG8_WAIT_L(0); PG8_BAR; PG8_MMA(1, 0, At, B0); PG8_MMA(1, 1, At, B1); PG8_BAR; PG8_SCHED;
;             PG8_LDB(B0, 1, 0); PG8_LDB(B1, 1, 1); PG8_SCHED; PG8_LDA(At, 1, 0); PG8_STAGE(PG8_SA(0, 1), a2 + hstepA, voffA);
;             PG8_WAIT_V(8); PG8_WAIT_L(0); PG8_BAR; PG8_MMA(0, 0, At, B0); PG8_MMA(0, 1, At, B1); PG8_BAR; PG8_SCHED;
;             PG8_LDA(At, 1, 1); PG8_STAGE(PG8_SB(1, 0), b3, voffB); PG8_STAGE(PG8_SB(1, 1), b3 + hstepB, voffB); PG8_STAGE(PG8_SA(1, 0), a3, voffA);
;             PG8_WAIT_V(8); PG8_WAIT_L(0); PG8_BAR; PG8_MMA(1, 0, At, B0); PG8_MMA(1, 1, At, B1); PG8_BAR; PG8_SCHED;
	s_add_i32 s10, s12, s8
	v_lshl_add_u64 v[130:131], v[130:131], 0, s[2:3]
	s_mov_b32 m0, s10
	ds_read_b128 v[214:217], v169 offset:49152
	ds_read_b128 v[218:221], v169 offset:50176
	ds_read_b128 v[222:225], v169 offset:51200
	ds_read_b128 v[226:229], v169 offset:52224
	ds_read_b128 v[230:233], v169 offset:53248
	ds_read_b128 v[234:237], v169 offset:54272
	ds_read_b128 v[238:241], v169 offset:55296
	ds_read_b128 v[242:245], v169 offset:56320
	global_load_lds_dwordx4 v[130:131], off
	s_add_i32 m0, s10, 0x2000
	s_add_u32 s10, s48, 0x100080
	v_lshl_add_u64 v[130:131], v[132:133], 0, s[2:3]
	s_addc_u32 s11, s49, 0
	s_add_i32 s12, s13, s8
	global_load_lds_dwordx4 v[130:131], off
	v_lshl_add_u64 v[130:131], s[10:11], 0, v[0:1]
	s_mov_b32 m0, s12
	s_nop 0
	global_load_lds_dwordx4 v[130:131], off
	v_lshl_add_u64 v[130:131], s[10:11], 0, v[150:151]
	s_add_i32 m0, s12, 0x2000
	s_nop 0
	global_load_lds_dwordx4 v[130:131], off
	v_lshl_add_u64 v[130:131], v[164:165], 0, s[2:3]
	s_mov_b32 m0, s35
	s_nop 0
	global_load_lds_dwordx4 v[130:131], off
	v_lshl_add_u64 v[130:131], v[246:247], 0, s[2:3]
	s_mov_b32 m0, s52
	s_nop 0
	global_load_lds_dwordx4 v[130:131], off
	s_waitcnt vmcnt(8)
	s_waitcnt lgkmcnt(0)
	s_barrier
	s_setprio 1
	s_waitcnt lgkmcnt(0)
	v_mfma_f32_16x16x32_bf16 v[62:65], v[160:163], v[214:217], v[62:65]
	v_mfma_f32_16x16x32_bf16 v[58:61], v[186:189], v[214:217], v[58:61]
	s_add_i32 s63, s63, 2
	v_mfma_f32_16x16x32_bf16 v[46:49], v[160:163], v[222:225], v[46:49]
	s_add_u32 s46, s46, 0x100
	v_mfma_f32_16x16x32_bf16 v[42:45], v[186:189], v[222:225], v[42:45]
	s_addc_u32 s47, s47, 0
	v_mfma_f32_16x16x32_bf16 v[30:33], v[160:163], v[230:233], v[30:33]
	s_add_u32 s57, s57, 0x100
	v_mfma_f32_16x16x32_bf16 v[26:29], v[186:189], v[230:233], v[26:29]
	s_addc_u32 s62, s62, 0
	v_mfma_f32_16x16x32_bf16 v[14:17], v[160:163], v[238:241], v[14:17]
	s_add_u32 s10, s46, 0xfff00080
	v_mfma_f32_16x16x32_bf16 v[10:13], v[186:189], v[238:241], v[10:13]
	s_addc_u32 s11, s47, -1
	v_mfma_f32_16x16x32_bf16 v[62:65], v[170:173], v[218:221], v[62:65]
	s_add_i32 s12, 0, 0x10000
	v_mfma_f32_16x16x32_bf16 v[58:61], v[190:193], v[218:221], v[58:61]
	s_cmp_eq_u32 s63, 60
	v_mfma_f32_16x16x32_bf16 v[46:49], v[170:173], v[226:229], v[46:49]
	s_cselect_b32 s51, s41, s11
	v_mfma_f32_16x16x32_bf16 v[42:45], v[190:193], v[226:229], v[42:45]
	s_cselect_b32 s50, s56, s10
	v_mfma_f32_16x16x32_bf16 v[30:33], v[170:173], v[234:237], v[30:33]
	v_add_u32_e32 v130, s12, v167
	v_mfma_f32_16x16x32_bf16 v[26:29], v[190:193], v[234:237], v[26:29]
	s_cselect_b32 s49, s4, s62
	v_mfma_f32_16x16x32_bf16 v[14:17], v[170:173], v[242:245], v[14:17]
	s_cselect_b32 s48, s39, s57
	v_mfma_f32_16x16x32_bf16 v[10:13], v[190:193], v[242:245], v[10:13]
	s_add_i32 s13, 0, 0x14000
	s_setprio 0
	s_setprio 1
	v_mfma_f32_16x16x32_bf16 v[54:57], v[198:201], v[214:217], v[54:57]
	s_cmp_gt_u32 s63, 61
	v_mfma_f32_16x16x32_bf16 v[50:53], v[206:209], v[214:217], v[50:53]
	v_mfma_f32_16x16x32_bf16 v[38:41], v[198:201], v[222:225], v[38:41]
	v_mfma_f32_16x16x32_bf16 v[34:37], v[206:209], v[222:225], v[34:37]
	v_mfma_f32_16x16x32_bf16 v[22:25], v[198:201], v[230:233], v[22:25]
	v_mfma_f32_16x16x32_bf16 v[18:21], v[206:209], v[230:233], v[18:21]
	v_mfma_f32_16x16x32_bf16 v[6:9], v[198:201], v[238:241], v[6:9]
	v_mfma_f32_16x16x32_bf16 v[2:5], v[206:209], v[238:241], v[2:5]
	v_mfma_f32_16x16x32_bf16 v[54:57], v[202:205], v[218:221], v[54:57]
	v_mfma_f32_16x16x32_bf16 v[50:53], v[210:213], v[218:221], v[50:53]
	v_mfma_f32_16x16x32_bf16 v[38:41], v[202:205], v[226:229], v[38:41]
	v_mfma_f32_16x16x32_bf16 v[34:37], v[210:213], v[226:229], v[34:37]
	v_mfma_f32_16x16x32_bf16 v[22:25], v[202:205], v[234:237], v[22:25]
	v_mfma_f32_16x16x32_bf16 v[18:21], v[210:213], v[234:237], v[18:21]
	v_mfma_f32_16x16x32_bf16 v[6:9], v[202:205], v[242:245], v[6:9]
	v_mfma_f32_16x16x32_bf16 v[2:5], v[210:213], v[242:245], v[2:5]
	s_setprio 0
	s_barrier
	s_cbranch_scc0 .Lgk_929
	s_and_b64 vcc, exec, s[20:21]
	s_mov_b64 s[62:63], s[14:15]
	s_cbranch_vccz .LBB0_932
	s_barrier
